# weight-tile conversion and silu(c) table: all row loads of a tile / all 18 conditioning values issued up front with counted vmcnt instead of one load per wait
# speedup vs baseline: 1.0503x; 1.0077x over previous
.LBB0_72:
	v_mov_b64_e32 v[144:145], 0
	v_mov_b64_e32 v[146:147], 0
	v_mov_b64_e32 v[148:149], 0
	v_mov_b64_e32 v[150:151], 0
	v_mov_b64_e32 v[152:153], 0
	v_mov_b64_e32 v[154:155], 0
	v_mov_b64_e32 v[156:157], 0
	v_mov_b64_e32 v[158:159], 0
	v_mov_b64_e32 v[160:161], 0
	v_mov_b64_e32 v[162:163], 0
	v_mov_b64_e32 v[164:165], 0
	v_mov_b64_e32 v[166:167], 0
	v_mov_b64_e32 v[168:169], 0
	v_mov_b64_e32 v[170:171], 0
	v_mov_b64_e32 v[172:173], 0
	v_mov_b64_e32 v[174:175], 0
	s_and_saveexec_b64 s[16:17], vcc
	v_mad_u64_u32 v[184:185], s[18:19], v10, v56, 0
	v_lshlrev_b32_e32 v186, 3, v56
	v_mov_b32_e32 v187, 0
	v_lshl_add_u64 v[184:185], v[184:185], 2, v[62:63]
	global_load_dwordx4 v[144:147], v[184:185], off
	v_lshl_add_u64 v[184:185], v[184:185], 0, v[186:187]
	global_load_dwordx4 v[148:151], v[184:185], off
	v_lshl_add_u64 v[184:185], v[184:185], 0, v[186:187]
	global_load_dwordx4 v[152:155], v[184:185], off
	v_lshl_add_u64 v[184:185], v[184:185], 0, v[186:187]
	global_load_dwordx4 v[156:159], v[184:185], off
	v_lshl_add_u64 v[184:185], v[184:185], 0, v[186:187]
	global_load_dwordx4 v[160:163], v[184:185], off
	v_lshl_add_u64 v[184:185], v[184:185], 0, v[186:187]
	global_load_dwordx4 v[164:167], v[184:185], off
	v_lshl_add_u64 v[184:185], v[184:185], 0, v[186:187]
	global_load_dwordx4 v[168:171], v[184:185], off
	v_lshl_add_u64 v[184:185], v[184:185], 0, v[186:187]
	global_load_dwordx4 v[172:175], v[184:185], off
	v_lshl_add_u64 v[184:185], v[184:185], 0, v[186:187]
	s_and_b64 s[18:19], exec, s[14:15]
	s_mov_b64 exec, s[18:19]
	v_lshlrev_b32_e32 v232, 2, v10
	v_mov_b32_e32 v233, 0
	v_lshl_add_u64 v[232:233], v[58:59], 0, v[232:233]
	global_load_dword v176, v[232:233], off
	global_load_dword v177, v[232:233], off offset:8
	global_load_dword v178, v[232:233], off offset:16
	global_load_dword v179, v[232:233], off offset:24
	global_load_dword v180, v[232:233], off offset:32
	global_load_dword v181, v[232:233], off offset:40
	global_load_dword v182, v[232:233], off offset:48
	global_load_dword v183, v[232:233], off offset:56
	s_waitcnt vmcnt(7)
	v_mul_f32_e32 v144, v176, v144
	v_mul_f32_e32 v145, v176, v145
	v_mul_f32_e32 v146, v176, v146
	v_mul_f32_e32 v147, v176, v147
	s_mov_b64 exec, s[16:17]
	v_cvt_pk_bf16_f32 v234, v144, v144
	ds_write_b16 v53, v234 offset:0
	v_cvt_pk_bf16_f32 v235, v145, v145
	ds_write_b16 v53, v235 offset:260
	v_cvt_pk_bf16_f32 v234, v146, v146
	ds_write_b16 v53, v234 offset:520
	v_cvt_pk_bf16_f32 v235, v147, v147
	ds_write_b16 v53, v235 offset:780
	s_waitcnt vmcnt(6)
	s_mov_b64 exec, s[18:19]
	v_mul_f32_e32 v148, v177, v148
	v_mul_f32_e32 v149, v177, v149
	v_mul_f32_e32 v150, v177, v150
	v_mul_f32_e32 v151, v177, v151
	s_mov_b64 exec, s[16:17]
	v_cvt_pk_bf16_f32 v234, v148, v148
	ds_write_b16 v53, v234 offset:4
	v_cvt_pk_bf16_f32 v235, v149, v149
	ds_write_b16 v53, v235 offset:264
	v_cvt_pk_bf16_f32 v234, v150, v150
	ds_write_b16 v53, v234 offset:524
	v_cvt_pk_bf16_f32 v235, v151, v151
	ds_write_b16 v53, v235 offset:784
	s_waitcnt vmcnt(5)
	s_mov_b64 exec, s[18:19]
	v_mul_f32_e32 v152, v178, v152
	v_mul_f32_e32 v153, v178, v153
	v_mul_f32_e32 v154, v178, v154
	v_mul_f32_e32 v155, v178, v155
	s_mov_b64 exec, s[16:17]
	v_cvt_pk_bf16_f32 v234, v152, v152
	ds_write_b16 v53, v234 offset:8
	v_cvt_pk_bf16_f32 v235, v153, v153
	ds_write_b16 v53, v235 offset:268
	v_cvt_pk_bf16_f32 v234, v154, v154
	ds_write_b16 v53, v234 offset:528
	v_cvt_pk_bf16_f32 v235, v155, v155
	ds_write_b16 v53, v235 offset:788
	s_waitcnt vmcnt(4)
	s_mov_b64 exec, s[18:19]
	v_mul_f32_e32 v156, v179, v156
	v_mul_f32_e32 v157, v179, v157
	v_mul_f32_e32 v158, v179, v158
	v_mul_f32_e32 v159, v179, v159
	s_mov_b64 exec, s[16:17]
	v_cvt_pk_bf16_f32 v234, v156, v156
	ds_write_b16 v53, v234 offset:12
	v_cvt_pk_bf16_f32 v235, v157, v157
	ds_write_b16 v53, v235 offset:272
	v_cvt_pk_bf16_f32 v234, v158, v158
	ds_write_b16 v53, v234 offset:532
	v_cvt_pk_bf16_f32 v235, v159, v159
	ds_write_b16 v53, v235 offset:792
	s_waitcnt vmcnt(3)
	s_mov_b64 exec, s[18:19]
	v_mul_f32_e32 v160, v180, v160
	v_mul_f32_e32 v161, v180, v161
	v_mul_f32_e32 v162, v180, v162
	v_mul_f32_e32 v163, v180, v163
	s_mov_b64 exec, s[16:17]
	v_cvt_pk_bf16_f32 v234, v160, v160
	ds_write_b16 v53, v234 offset:16
	v_cvt_pk_bf16_f32 v235, v161, v161
	ds_write_b16 v53, v235 offset:276
	v_cvt_pk_bf16_f32 v234, v162, v162
	ds_write_b16 v53, v234 offset:536
	v_cvt_pk_bf16_f32 v235, v163, v163
	ds_write_b16 v53, v235 offset:796
	s_waitcnt vmcnt(2)
	s_mov_b64 exec, s[18:19]
	v_mul_f32_e32 v164, v181, v164
	v_mul_f32_e32 v165, v181, v165
	v_mul_f32_e32 v166, v181, v166
	v_mul_f32_e32 v167, v181, v167
	s_mov_b64 exec, s[16:17]
	v_cvt_pk_bf16_f32 v234, v164, v164
	ds_write_b16 v53, v234 offset:20
	v_cvt_pk_bf16_f32 v235, v165, v165
	ds_write_b16 v53, v235 offset:280
	v_cvt_pk_bf16_f32 v234, v166, v166
	ds_write_b16 v53, v234 offset:540
	v_cvt_pk_bf16_f32 v235, v167, v167
	ds_write_b16 v53, v235 offset:800
	s_waitcnt vmcnt(1)
	s_mov_b64 exec, s[18:19]
	v_mul_f32_e32 v168, v182, v168
	v_mul_f32_e32 v169, v182, v169
	v_mul_f32_e32 v170, v182, v170
	v_mul_f32_e32 v171, v182, v171
	s_mov_b64 exec, s[16:17]
	v_cvt_pk_bf16_f32 v234, v168, v168
	ds_write_b16 v53, v234 offset:24
	v_cvt_pk_bf16_f32 v235, v169, v169
	ds_write_b16 v53, v235 offset:284
	v_cvt_pk_bf16_f32 v234, v170, v170
	ds_write_b16 v53, v234 offset:544
	v_cvt_pk_bf16_f32 v235, v171, v171
	ds_write_b16 v53, v235 offset:804
	s_waitcnt vmcnt(0)
	s_mov_b64 exec, s[18:19]
	v_mul_f32_e32 v172, v183, v172
	v_mul_f32_e32 v173, v183, v173
	v_mul_f32_e32 v174, v183, v174
	v_mul_f32_e32 v175, v183, v175
	s_mov_b64 exec, s[16:17]
	v_cvt_pk_bf16_f32 v234, v172, v172
	ds_write_b16 v53, v234 offset:28
	v_cvt_pk_bf16_f32 v235, v173, v173
	ds_write_b16 v53, v235 offset:288
	v_cvt_pk_bf16_f32 v234, v174, v174
	ds_write_b16 v53, v234 offset:548
	v_cvt_pk_bf16_f32 v235, v175, v175
	ds_write_b16 v53, v235 offset:808
	v_mov_b64_e32 v[144:145], 0
	v_mov_b64_e32 v[146:147], 0
	v_mov_b64_e32 v[148:149], 0
	v_mov_b64_e32 v[150:151], 0
	v_mov_b64_e32 v[152:153], 0
	v_mov_b64_e32 v[154:155], 0
	v_mov_b64_e32 v[156:157], 0
	v_mov_b64_e32 v[158:159], 0
	v_mov_b64_e32 v[160:161], 0
	v_mov_b64_e32 v[162:163], 0
	v_mov_b64_e32 v[164:165], 0
	v_mov_b64_e32 v[166:167], 0
	v_mov_b64_e32 v[168:169], 0
	v_mov_b64_e32 v[170:171], 0
	v_mov_b64_e32 v[172:173], 0
	v_mov_b64_e32 v[174:175], 0
	s_and_saveexec_b64 s[16:17], vcc
	global_load_dwordx4 v[144:147], v[184:185], off
	v_lshl_add_u64 v[184:185], v[184:185], 0, v[186:187]
	global_load_dwordx4 v[148:151], v[184:185], off
	v_lshl_add_u64 v[184:185], v[184:185], 0, v[186:187]
	global_load_dwordx4 v[152:155], v[184:185], off
	v_lshl_add_u64 v[184:185], v[184:185], 0, v[186:187]
	global_load_dwordx4 v[156:159], v[184:185], off
	v_lshl_add_u64 v[184:185], v[184:185], 0, v[186:187]
	global_load_dwordx4 v[160:163], v[184:185], off
	v_lshl_add_u64 v[184:185], v[184:185], 0, v[186:187]
	global_load_dwordx4 v[164:167], v[184:185], off
	v_lshl_add_u64 v[184:185], v[184:185], 0, v[186:187]
	global_load_dwordx4 v[168:171], v[184:185], off
	v_lshl_add_u64 v[184:185], v[184:185], 0, v[186:187]
	global_load_dwordx4 v[172:175], v[184:185], off
	v_lshl_add_u64 v[184:185], v[184:185], 0, v[186:187]
	s_and_b64 s[18:19], exec, s[14:15]
	s_mov_b64 exec, s[18:19]
	global_load_dword v176, v[232:233], off offset:64
	global_load_dword v177, v[232:233], off offset:72
	global_load_dword v178, v[232:233], off offset:80
	global_load_dword v179, v[232:233], off offset:88
	global_load_dword v180, v[232:233], off offset:96
	global_load_dword v181, v[232:233], off offset:104
	global_load_dword v182, v[232:233], off offset:112
	global_load_dword v183, v[232:233], off offset:120
	s_waitcnt vmcnt(7)
	v_mul_f32_e32 v144, v176, v144
	v_mul_f32_e32 v145, v176, v145
	v_mul_f32_e32 v146, v176, v146
	v_mul_f32_e32 v147, v176, v147
	s_mov_b64 exec, s[16:17]
	v_cvt_pk_bf16_f32 v234, v144, v144
	ds_write_b16 v53, v234 offset:32
	v_cvt_pk_bf16_f32 v235, v145, v145
	ds_write_b16 v53, v235 offset:292
	v_cvt_pk_bf16_f32 v234, v146, v146
	ds_write_b16 v53, v234 offset:552
	v_cvt_pk_bf16_f32 v235, v147, v147
	ds_write_b16 v53, v235 offset:812
	s_waitcnt vmcnt(6)
	s_mov_b64 exec, s[18:19]
	v_mul_f32_e32 v148, v177, v148
	v_mul_f32_e32 v149, v177, v149
	v_mul_f32_e32 v150, v177, v150
	v_mul_f32_e32 v151, v177, v151
	s_mov_b64 exec, s[16:17]
	v_cvt_pk_bf16_f32 v234, v148, v148
	ds_write_b16 v53, v234 offset:36
	v_cvt_pk_bf16_f32 v235, v149, v149
	ds_write_b16 v53, v235 offset:296
	v_cvt_pk_bf16_f32 v234, v150, v150
	ds_write_b16 v53, v234 offset:556
	v_cvt_pk_bf16_f32 v235, v151, v151
	ds_write_b16 v53, v235 offset:816
	s_waitcnt vmcnt(5)
	s_mov_b64 exec, s[18:19]
	v_mul_f32_e32 v152, v178, v152
	v_mul_f32_e32 v153, v178, v153
	v_mul_f32_e32 v154, v178, v154
	v_mul_f32_e32 v155, v178, v155
	s_mov_b64 exec, s[16:17]
	v_cvt_pk_bf16_f32 v234, v152, v152
	ds_write_b16 v53, v234 offset:40
	v_cvt_pk_bf16_f32 v235, v153, v153
	ds_write_b16 v53, v235 offset:300
	v_cvt_pk_bf16_f32 v234, v154, v154
	ds_write_b16 v53, v234 offset:560
	v_cvt_pk_bf16_f32 v235, v155, v155
	ds_write_b16 v53, v235 offset:820
	s_waitcnt vmcnt(4)
	s_mov_b64 exec, s[18:19]
	v_mul_f32_e32 v156, v179, v156
	v_mul_f32_e32 v157, v179, v157
	v_mul_f32_e32 v158, v179, v158
	v_mul_f32_e32 v159, v179, v159
	s_mov_b64 exec, s[16:17]
	v_cvt_pk_bf16_f32 v234, v156, v156
	ds_write_b16 v53, v234 offset:44
	v_cvt_pk_bf16_f32 v235, v157, v157
	ds_write_b16 v53, v235 offset:304
	v_cvt_pk_bf16_f32 v234, v158, v158
	ds_write_b16 v53, v234 offset:564
	v_cvt_pk_bf16_f32 v235, v159, v159
	ds_write_b16 v53, v235 offset:824
	s_waitcnt vmcnt(3)
	s_mov_b64 exec, s[18:19]
	v_mul_f32_e32 v160, v180, v160
	v_mul_f32_e32 v161, v180, v161
	v_mul_f32_e32 v162, v180, v162
	v_mul_f32_e32 v163, v180, v163
	s_mov_b64 exec, s[16:17]
	v_cvt_pk_bf16_f32 v234, v160, v160
	ds_write_b16 v53, v234 offset:48
	v_cvt_pk_bf16_f32 v235, v161, v161
	ds_write_b16 v53, v235 offset:308
	v_cvt_pk_bf16_f32 v234, v162, v162
	ds_write_b16 v53, v234 offset:568
	v_cvt_pk_bf16_f32 v235, v163, v163
	ds_write_b16 v53, v235 offset:828
	s_waitcnt vmcnt(2)
	s_mov_b64 exec, s[18:19]
	v_mul_f32_e32 v164, v181, v164
	v_mul_f32_e32 v165, v181, v165
	v_mul_f32_e32 v166, v181, v166
	v_mul_f32_e32 v167, v181, v167
	s_mov_b64 exec, s[16:17]
	v_cvt_pk_bf16_f32 v234, v164, v164
	ds_write_b16 v53, v234 offset:52
	v_cvt_pk_bf16_f32 v235, v165, v165
	ds_write_b16 v53, v235 offset:312
	v_cvt_pk_bf16_f32 v234, v166, v166
	ds_write_b16 v53, v234 offset:572
	v_cvt_pk_bf16_f32 v235, v167, v167
	ds_write_b16 v53, v235 offset:832
	s_waitcnt vmcnt(1)
	s_mov_b64 exec, s[18:19]
	v_mul_f32_e32 v168, v182, v168
	v_mul_f32_e32 v169, v182, v169
	v_mul_f32_e32 v170, v182, v170
	v_mul_f32_e32 v171, v182, v171
	s_mov_b64 exec, s[16:17]
	v_cvt_pk_bf16_f32 v234, v168, v168
	ds_write_b16 v53, v234 offset:56
	v_cvt_pk_bf16_f32 v235, v169, v169
	ds_write_b16 v53, v235 offset:316
	v_cvt_pk_bf16_f32 v234, v170, v170
	ds_write_b16 v53, v234 offset:576
	v_cvt_pk_bf16_f32 v235, v171, v171
	ds_write_b16 v53, v235 offset:836
	s_waitcnt vmcnt(0)
	s_mov_b64 exec, s[18:19]
	v_mul_f32_e32 v172, v183, v172
	v_mul_f32_e32 v173, v183, v173
	v_mul_f32_e32 v174, v183, v174
	v_mul_f32_e32 v175, v183, v175
	s_mov_b64 exec, s[16:17]
	v_cvt_pk_bf16_f32 v234, v172, v172
	ds_write_b16 v53, v234 offset:60
	v_cvt_pk_bf16_f32 v235, v173, v173
	ds_write_b16 v53, v235 offset:320
	v_cvt_pk_bf16_f32 v234, v174, v174
	ds_write_b16 v53, v234 offset:580
	v_cvt_pk_bf16_f32 v235, v175, v175
	ds_write_b16 v53, v235 offset:840
	s_mov_b32 s20, 32
	v_add_u32_e32 v53, 64, v53
	v_lshl_add_u64 v[64:65], v[64:65], 0, 64
	v_lshl_add_u64 v[64:65], v[64:65], 0, 64
	s_branch .LBB0_103

.LBB0_104:
	s_mov_b64 s[14:15], exec
	v_lshlrev_b32_e32 v160, 2, v128
	v_lshlrev_b32_e32 v161, 2, v128
	v_mul_u32_u24_e32 v162, 48, v128
	global_load_dword v142, v160, s[54:55]
	global_load_dword v143, v160, s[54:55] offset:2048
	v_add_u32_e32 v160, 0x1000, v160
	global_load_dword v144, v160, s[54:55]
	global_load_dword v145, v160, s[54:55] offset:2048
	v_add_u32_e32 v160, 0x1000, v160
	global_load_dword v146, v160, s[54:55]
	global_load_dword v147, v160, s[54:55] offset:2048
	v_add_u32_e32 v160, 0x1000, v160
	global_load_dword v148, v160, s[54:55]
	global_load_dword v149, v160, s[54:55] offset:2048
	v_add_u32_e32 v160, 0x1000, v160
	global_load_dword v150, v160, s[54:55]
	global_load_dword v151, v160, s[54:55] offset:2048
	v_add_u32_e32 v160, 0x1000, v160
	global_load_dword v152, v160, s[54:55]
	global_load_dword v153, v160, s[54:55] offset:2048
	v_add_u32_e32 v160, 0x1000, v160
	global_load_dword v154, v160, s[54:55]
	global_load_dword v155, v160, s[54:55] offset:2048
	v_add_u32_e32 v160, 0x1000, v160
	global_load_dword v156, v160, s[54:55]
	global_load_dword v157, v160, s[54:55] offset:2048
	global_load_dword v158, v161, s[58:59]
	global_load_dword v159, v161, s[58:59] offset:2048
	s_waitcnt vmcnt(17)
	v_mul_f32_e32 v7, 0xbfb8aa3b, v142
	v_fma_f32 v10, v142, s30, -v7
	v_rndne_f32_e32 v51, v7
	v_fmac_f32_e32 v10, 0xb2a5705f, v142
	v_sub_f32_e32 v7, v7, v51
	v_add_f32_e32 v7, v7, v10
	v_cvt_i32_f32_e32 v51, v51
	v_exp_f32_e32 v7, v7
	v_cmp_nlt_f32_e32 vcc, s31, v142
	v_ldexp_f32 v7, v7, v51
	s_nop 0
	v_cndmask_b32_e32 v7, 0, v7, vcc
	v_cmp_ngt_f32_e32 vcc, s33, v142
	s_nop 1
	v_cndmask_b32_e32 v7, v120, v7, vcc
	v_add_f32_e32 v7, 1.0, v7
	v_div_scale_f32 v10, s[18:19], v7, v7, v142
	v_rcp_f32_e32 v51, v10
	v_div_scale_f32 v52, vcc, v142, v7, v142
	v_fma_f32 v53, -v10, v51, 1.0
	v_fmac_f32_e32 v51, v53, v51
	v_mul_f32_e32 v53, v52, v51
	v_fma_f32 v54, -v10, v53, v52
	v_fmac_f32_e32 v53, v54, v51
	v_fma_f32 v10, -v10, v53, v52
	v_div_fmas_f32 v10, v10, v51, v53
	v_div_fixup_f32 v6, v10, v7, v142
	ds_write_b32 v162, v6 offset:0
	s_waitcnt vmcnt(16)
	v_mul_f32_e32 v7, 0xbfb8aa3b, v143
	v_fma_f32 v10, v143, s30, -v7
	v_rndne_f32_e32 v51, v7
	v_fmac_f32_e32 v10, 0xb2a5705f, v143
	v_sub_f32_e32 v7, v7, v51
	v_add_f32_e32 v7, v7, v10
	v_cvt_i32_f32_e32 v51, v51
	v_exp_f32_e32 v7, v7
	v_cmp_nlt_f32_e32 vcc, s31, v143
	v_ldexp_f32 v7, v7, v51
	s_nop 0
	v_cndmask_b32_e32 v7, 0, v7, vcc
	v_cmp_ngt_f32_e32 vcc, s33, v143
	s_nop 1
	v_cndmask_b32_e32 v7, v120, v7, vcc
	v_add_f32_e32 v7, 1.0, v7
	v_div_scale_f32 v10, s[18:19], v7, v7, v143
	v_rcp_f32_e32 v51, v10
	v_div_scale_f32 v52, vcc, v143, v7, v143
	v_fma_f32 v53, -v10, v51, 1.0
	v_fmac_f32_e32 v51, v53, v51
	v_mul_f32_e32 v53, v52, v51
	v_fma_f32 v54, -v10, v53, v52
	v_fmac_f32_e32 v53, v54, v51
	v_fma_f32 v10, -v10, v53, v52
	v_div_fmas_f32 v10, v10, v51, v53
	v_div_fixup_f32 v6, v10, v7, v143
	ds_write_b32 v162, v6 offset:24576
	s_waitcnt vmcnt(15)
	v_mul_f32_e32 v7, 0xbfb8aa3b, v144
	v_fma_f32 v10, v144, s30, -v7
	v_rndne_f32_e32 v51, v7
	v_fmac_f32_e32 v10, 0xb2a5705f, v144
	v_sub_f32_e32 v7, v7, v51
	v_add_f32_e32 v7, v7, v10
	v_cvt_i32_f32_e32 v51, v51
	v_exp_f32_e32 v7, v7
	v_cmp_nlt_f32_e32 vcc, s31, v144
	v_ldexp_f32 v7, v7, v51
	s_nop 0
	v_cndmask_b32_e32 v7, 0, v7, vcc
	v_cmp_ngt_f32_e32 vcc, s33, v144
	s_nop 1
	v_cndmask_b32_e32 v7, v120, v7, vcc
	v_add_f32_e32 v7, 1.0, v7
	v_div_scale_f32 v10, s[18:19], v7, v7, v144
	v_rcp_f32_e32 v51, v10
	v_div_scale_f32 v52, vcc, v144, v7, v144
	v_fma_f32 v53, -v10, v51, 1.0
	v_fmac_f32_e32 v51, v53, v51
	v_mul_f32_e32 v53, v52, v51
	v_fma_f32 v54, -v10, v53, v52
	v_fmac_f32_e32 v53, v54, v51
	v_fma_f32 v10, -v10, v53, v52
	v_div_fmas_f32 v10, v10, v51, v53
	v_div_fixup_f32 v6, v10, v7, v144
	ds_write_b32 v162, v6 offset:4
	s_waitcnt vmcnt(14)
	v_mul_f32_e32 v7, 0xbfb8aa3b, v145
	v_fma_f32 v10, v145, s30, -v7
	v_rndne_f32_e32 v51, v7
	v_fmac_f32_e32 v10, 0xb2a5705f, v145
	v_sub_f32_e32 v7, v7, v51
	v_add_f32_e32 v7, v7, v10
	v_cvt_i32_f32_e32 v51, v51
	v_exp_f32_e32 v7, v7
	v_cmp_nlt_f32_e32 vcc, s31, v145
	v_ldexp_f32 v7, v7, v51
	s_nop 0
	v_cndmask_b32_e32 v7, 0, v7, vcc
	v_cmp_ngt_f32_e32 vcc, s33, v145
	s_nop 1
	v_cndmask_b32_e32 v7, v120, v7, vcc
	v_add_f32_e32 v7, 1.0, v7
	v_div_scale_f32 v10, s[18:19], v7, v7, v145
	v_rcp_f32_e32 v51, v10
	v_div_scale_f32 v52, vcc, v145, v7, v145
	v_fma_f32 v53, -v10, v51, 1.0
	v_fmac_f32_e32 v51, v53, v51
	v_mul_f32_e32 v53, v52, v51
	v_fma_f32 v54, -v10, v53, v52
	v_fmac_f32_e32 v53, v54, v51
	v_fma_f32 v10, -v10, v53, v52
	v_div_fmas_f32 v10, v10, v51, v53
	v_div_fixup_f32 v6, v10, v7, v145
	ds_write_b32 v162, v6 offset:24580
	s_waitcnt vmcnt(13)
	v_mul_f32_e32 v7, 0xbfb8aa3b, v146
	v_fma_f32 v10, v146, s30, -v7
	v_rndne_f32_e32 v51, v7
	v_fmac_f32_e32 v10, 0xb2a5705f, v146
	v_sub_f32_e32 v7, v7, v51
	v_add_f32_e32 v7, v7, v10
	v_cvt_i32_f32_e32 v51, v51
	v_exp_f32_e32 v7, v7
	v_cmp_nlt_f32_e32 vcc, s31, v146
	v_ldexp_f32 v7, v7, v51
	s_nop 0
	v_cndmask_b32_e32 v7, 0, v7, vcc
	v_cmp_ngt_f32_e32 vcc, s33, v146
	s_nop 1
	v_cndmask_b32_e32 v7, v120, v7, vcc
	v_add_f32_e32 v7, 1.0, v7
	v_div_scale_f32 v10, s[18:19], v7, v7, v146
	v_rcp_f32_e32 v51, v10
	v_div_scale_f32 v52, vcc, v146, v7, v146
	v_fma_f32 v53, -v10, v51, 1.0
	v_fmac_f32_e32 v51, v53, v51
	v_mul_f32_e32 v53, v52, v51
	v_fma_f32 v54, -v10, v53, v52
	v_fmac_f32_e32 v53, v54, v51
	v_fma_f32 v10, -v10, v53, v52
	v_div_fmas_f32 v10, v10, v51, v53
	v_div_fixup_f32 v6, v10, v7, v146
	ds_write_b32 v162, v6 offset:8
	s_waitcnt vmcnt(12)
	v_mul_f32_e32 v7, 0xbfb8aa3b, v147
	v_fma_f32 v10, v147, s30, -v7
	v_rndne_f32_e32 v51, v7
	v_fmac_f32_e32 v10, 0xb2a5705f, v147
	v_sub_f32_e32 v7, v7, v51
	v_add_f32_e32 v7, v7, v10
	v_cvt_i32_f32_e32 v51, v51
	v_exp_f32_e32 v7, v7
	v_cmp_nlt_f32_e32 vcc, s31, v147
	v_ldexp_f32 v7, v7, v51
	s_nop 0
	v_cndmask_b32_e32 v7, 0, v7, vcc
	v_cmp_ngt_f32_e32 vcc, s33, v147
	s_nop 1
	v_cndmask_b32_e32 v7, v120, v7, vcc
	v_add_f32_e32 v7, 1.0, v7
	v_div_scale_f32 v10, s[18:19], v7, v7, v147
	v_rcp_f32_e32 v51, v10
	v_div_scale_f32 v52, vcc, v147, v7, v147
	v_fma_f32 v53, -v10, v51, 1.0
	v_fmac_f32_e32 v51, v53, v51
	v_mul_f32_e32 v53, v52, v51
	v_fma_f32 v54, -v10, v53, v52
	v_fmac_f32_e32 v53, v54, v51
	v_fma_f32 v10, -v10, v53, v52
	v_div_fmas_f32 v10, v10, v51, v53
	v_div_fixup_f32 v6, v10, v7, v147
	ds_write_b32 v162, v6 offset:24584
	s_waitcnt vmcnt(11)
	v_mul_f32_e32 v7, 0xbfb8aa3b, v148
	v_fma_f32 v10, v148, s30, -v7
	v_rndne_f32_e32 v51, v7
	v_fmac_f32_e32 v10, 0xb2a5705f, v148
	v_sub_f32_e32 v7, v7, v51
	v_add_f32_e32 v7, v7, v10
	v_cvt_i32_f32_e32 v51, v51
	v_exp_f32_e32 v7, v7
	v_cmp_nlt_f32_e32 vcc, s31, v148
	v_ldexp_f32 v7, v7, v51
	s_nop 0
	v_cndmask_b32_e32 v7, 0, v7, vcc
	v_cmp_ngt_f32_e32 vcc, s33, v148
	s_nop 1
	v_cndmask_b32_e32 v7, v120, v7, vcc
	v_add_f32_e32 v7, 1.0, v7
	v_div_scale_f32 v10, s[18:19], v7, v7, v148
	v_rcp_f32_e32 v51, v10
	v_div_scale_f32 v52, vcc, v148, v7, v148
	v_fma_f32 v53, -v10, v51, 1.0
	v_fmac_f32_e32 v51, v53, v51
	v_mul_f32_e32 v53, v52, v51
	v_fma_f32 v54, -v10, v53, v52
	v_fmac_f32_e32 v53, v54, v51
	v_fma_f32 v10, -v10, v53, v52
	v_div_fmas_f32 v10, v10, v51, v53
	v_div_fixup_f32 v6, v10, v7, v148
	ds_write_b32 v162, v6 offset:12
	s_waitcnt vmcnt(10)
	v_mul_f32_e32 v7, 0xbfb8aa3b, v149
	v_fma_f32 v10, v149, s30, -v7
	v_rndne_f32_e32 v51, v7
	v_fmac_f32_e32 v10, 0xb2a5705f, v149
	v_sub_f32_e32 v7, v7, v51
	v_add_f32_e32 v7, v7, v10
	v_cvt_i32_f32_e32 v51, v51
	v_exp_f32_e32 v7, v7
	v_cmp_nlt_f32_e32 vcc, s31, v149
	v_ldexp_f32 v7, v7, v51
	s_nop 0
	v_cndmask_b32_e32 v7, 0, v7, vcc
	v_cmp_ngt_f32_e32 vcc, s33, v149
	s_nop 1
	v_cndmask_b32_e32 v7, v120, v7, vcc
	v_add_f32_e32 v7, 1.0, v7
	v_div_scale_f32 v10, s[18:19], v7, v7, v149
	v_rcp_f32_e32 v51, v10
	v_div_scale_f32 v52, vcc, v149, v7, v149
	v_fma_f32 v53, -v10, v51, 1.0
	v_fmac_f32_e32 v51, v53, v51
	v_mul_f32_e32 v53, v52, v51
	v_fma_f32 v54, -v10, v53, v52
	v_fmac_f32_e32 v53, v54, v51
	v_fma_f32 v10, -v10, v53, v52
	v_div_fmas_f32 v10, v10, v51, v53
	v_div_fixup_f32 v6, v10, v7, v149
	ds_write_b32 v162, v6 offset:24588
	s_waitcnt vmcnt(9)
	v_mul_f32_e32 v7, 0xbfb8aa3b, v150
	v_fma_f32 v10, v150, s30, -v7
	v_rndne_f32_e32 v51, v7
	v_fmac_f32_e32 v10, 0xb2a5705f, v150
	v_sub_f32_e32 v7, v7, v51
	v_add_f32_e32 v7, v7, v10
	v_cvt_i32_f32_e32 v51, v51
	v_exp_f32_e32 v7, v7
	v_cmp_nlt_f32_e32 vcc, s31, v150
	v_ldexp_f32 v7, v7, v51
	s_nop 0
	v_cndmask_b32_e32 v7, 0, v7, vcc
	v_cmp_ngt_f32_e32 vcc, s33, v150
	s_nop 1
	v_cndmask_b32_e32 v7, v120, v7, vcc
	v_add_f32_e32 v7, 1.0, v7
	v_div_scale_f32 v10, s[18:19], v7, v7, v150
	v_rcp_f32_e32 v51, v10
	v_div_scale_f32 v52, vcc, v150, v7, v150
	v_fma_f32 v53, -v10, v51, 1.0
	v_fmac_f32_e32 v51, v53, v51
	v_mul_f32_e32 v53, v52, v51
	v_fma_f32 v54, -v10, v53, v52
	v_fmac_f32_e32 v53, v54, v51
	v_fma_f32 v10, -v10, v53, v52
	v_div_fmas_f32 v10, v10, v51, v53
	v_div_fixup_f32 v6, v10, v7, v150
	ds_write_b32 v162, v6 offset:16
	s_waitcnt vmcnt(8)
	v_mul_f32_e32 v7, 0xbfb8aa3b, v151
	v_fma_f32 v10, v151, s30, -v7
	v_rndne_f32_e32 v51, v7
	v_fmac_f32_e32 v10, 0xb2a5705f, v151
	v_sub_f32_e32 v7, v7, v51
	v_add_f32_e32 v7, v7, v10
	v_cvt_i32_f32_e32 v51, v51
	v_exp_f32_e32 v7, v7
	v_cmp_nlt_f32_e32 vcc, s31, v151
	v_ldexp_f32 v7, v7, v51
	s_nop 0
	v_cndmask_b32_e32 v7, 0, v7, vcc
	v_cmp_ngt_f32_e32 vcc, s33, v151
	s_nop 1
	v_cndmask_b32_e32 v7, v120, v7, vcc
	v_add_f32_e32 v7, 1.0, v7
	v_div_scale_f32 v10, s[18:19], v7, v7, v151
	v_rcp_f32_e32 v51, v10
	v_div_scale_f32 v52, vcc, v151, v7, v151
	v_fma_f32 v53, -v10, v51, 1.0
	v_fmac_f32_e32 v51, v53, v51
	v_mul_f32_e32 v53, v52, v51
	v_fma_f32 v54, -v10, v53, v52
	v_fmac_f32_e32 v53, v54, v51
	v_fma_f32 v10, -v10, v53, v52
	v_div_fmas_f32 v10, v10, v51, v53
	v_div_fixup_f32 v6, v10, v7, v151
	ds_write_b32 v162, v6 offset:24592
	s_waitcnt vmcnt(7)
	v_mul_f32_e32 v7, 0xbfb8aa3b, v152
	v_fma_f32 v10, v152, s30, -v7
	v_rndne_f32_e32 v51, v7
	v_fmac_f32_e32 v10, 0xb2a5705f, v152
	v_sub_f32_e32 v7, v7, v51
	v_add_f32_e32 v7, v7, v10
	v_cvt_i32_f32_e32 v51, v51
	v_exp_f32_e32 v7, v7
	v_cmp_nlt_f32_e32 vcc, s31, v152
	v_ldexp_f32 v7, v7, v51
	s_nop 0
	v_cndmask_b32_e32 v7, 0, v7, vcc
	v_cmp_ngt_f32_e32 vcc, s33, v152
	s_nop 1
	v_cndmask_b32_e32 v7, v120, v7, vcc
	v_add_f32_e32 v7, 1.0, v7
	v_div_scale_f32 v10, s[18:19], v7, v7, v152
	v_rcp_f32_e32 v51, v10
	v_div_scale_f32 v52, vcc, v152, v7, v152
	v_fma_f32 v53, -v10, v51, 1.0
	v_fmac_f32_e32 v51, v53, v51
	v_mul_f32_e32 v53, v52, v51
	v_fma_f32 v54, -v10, v53, v52
	v_fmac_f32_e32 v53, v54, v51
	v_fma_f32 v10, -v10, v53, v52
	v_div_fmas_f32 v10, v10, v51, v53
	v_div_fixup_f32 v6, v10, v7, v152
	ds_write_b32 v162, v6 offset:20
	s_waitcnt vmcnt(6)
	v_mul_f32_e32 v7, 0xbfb8aa3b, v153
	v_fma_f32 v10, v153, s30, -v7
	v_rndne_f32_e32 v51, v7
	v_fmac_f32_e32 v10, 0xb2a5705f, v153
	v_sub_f32_e32 v7, v7, v51
	v_add_f32_e32 v7, v7, v10
	v_cvt_i32_f32_e32 v51, v51
	v_exp_f32_e32 v7, v7
	v_cmp_nlt_f32_e32 vcc, s31, v153
	v_ldexp_f32 v7, v7, v51
	s_nop 0
	v_cndmask_b32_e32 v7, 0, v7, vcc
	v_cmp_ngt_f32_e32 vcc, s33, v153
	s_nop 1
	v_cndmask_b32_e32 v7, v120, v7, vcc
	v_add_f32_e32 v7, 1.0, v7
	v_div_scale_f32 v10, s[18:19], v7, v7, v153
	v_rcp_f32_e32 v51, v10
	v_div_scale_f32 v52, vcc, v153, v7, v153
	v_fma_f32 v53, -v10, v51, 1.0
	v_fmac_f32_e32 v51, v53, v51
	v_mul_f32_e32 v53, v52, v51
	v_fma_f32 v54, -v10, v53, v52
	v_fmac_f32_e32 v53, v54, v51
	v_fma_f32 v10, -v10, v53, v52
	v_div_fmas_f32 v10, v10, v51, v53
	v_div_fixup_f32 v6, v10, v7, v153
	ds_write_b32 v162, v6 offset:24596
	s_waitcnt vmcnt(5)
	v_mul_f32_e32 v7, 0xbfb8aa3b, v154
	v_fma_f32 v10, v154, s30, -v7
	v_rndne_f32_e32 v51, v7
	v_fmac_f32_e32 v10, 0xb2a5705f, v154
	v_sub_f32_e32 v7, v7, v51
	v_add_f32_e32 v7, v7, v10
	v_cvt_i32_f32_e32 v51, v51
	v_exp_f32_e32 v7, v7
	v_cmp_nlt_f32_e32 vcc, s31, v154
	v_ldexp_f32 v7, v7, v51
	s_nop 0
	v_cndmask_b32_e32 v7, 0, v7, vcc
	v_cmp_ngt_f32_e32 vcc, s33, v154
	s_nop 1
	v_cndmask_b32_e32 v7, v120, v7, vcc
	v_add_f32_e32 v7, 1.0, v7
	v_div_scale_f32 v10, s[18:19], v7, v7, v154
	v_rcp_f32_e32 v51, v10
	v_div_scale_f32 v52, vcc, v154, v7, v154
	v_fma_f32 v53, -v10, v51, 1.0
	v_fmac_f32_e32 v51, v53, v51
	v_mul_f32_e32 v53, v52, v51
	v_fma_f32 v54, -v10, v53, v52
	v_fmac_f32_e32 v53, v54, v51
	v_fma_f32 v10, -v10, v53, v52
	v_div_fmas_f32 v10, v10, v51, v53
	v_div_fixup_f32 v6, v10, v7, v154
	ds_write_b32 v162, v6 offset:24
	s_waitcnt vmcnt(4)
	v_mul_f32_e32 v7, 0xbfb8aa3b, v155
	v_fma_f32 v10, v155, s30, -v7
	v_rndne_f32_e32 v51, v7
	v_fmac_f32_e32 v10, 0xb2a5705f, v155
	v_sub_f32_e32 v7, v7, v51
	v_add_f32_e32 v7, v7, v10
	v_cvt_i32_f32_e32 v51, v51
	v_exp_f32_e32 v7, v7
	v_cmp_nlt_f32_e32 vcc, s31, v155
	v_ldexp_f32 v7, v7, v51
	s_nop 0
	v_cndmask_b32_e32 v7, 0, v7, vcc
	v_cmp_ngt_f32_e32 vcc, s33, v155
	s_nop 1
	v_cndmask_b32_e32 v7, v120, v7, vcc
	v_add_f32_e32 v7, 1.0, v7
	v_div_scale_f32 v10, s[18:19], v7, v7, v155
	v_rcp_f32_e32 v51, v10
	v_div_scale_f32 v52, vcc, v155, v7, v155
	v_fma_f32 v53, -v10, v51, 1.0
	v_fmac_f32_e32 v51, v53, v51
	v_mul_f32_e32 v53, v52, v51
	v_fma_f32 v54, -v10, v53, v52
	v_fmac_f32_e32 v53, v54, v51
	v_fma_f32 v10, -v10, v53, v52
	v_div_fmas_f32 v10, v10, v51, v53
	v_div_fixup_f32 v6, v10, v7, v155
	ds_write_b32 v162, v6 offset:24600
	s_waitcnt vmcnt(3)
	v_mul_f32_e32 v7, 0xbfb8aa3b, v156
	v_fma_f32 v10, v156, s30, -v7
	v_rndne_f32_e32 v51, v7
	v_fmac_f32_e32 v10, 0xb2a5705f, v156
	v_sub_f32_e32 v7, v7, v51
	v_add_f32_e32 v7, v7, v10
	v_cvt_i32_f32_e32 v51, v51
	v_exp_f32_e32 v7, v7
	v_cmp_nlt_f32_e32 vcc, s31, v156
	v_ldexp_f32 v7, v7, v51
	s_nop 0
	v_cndmask_b32_e32 v7, 0, v7, vcc
	v_cmp_ngt_f32_e32 vcc, s33, v156
	s_nop 1
	v_cndmask_b32_e32 v7, v120, v7, vcc
	v_add_f32_e32 v7, 1.0, v7
	v_div_scale_f32 v10, s[18:19], v7, v7, v156
	v_rcp_f32_e32 v51, v10
	v_div_scale_f32 v52, vcc, v156, v7, v156
	v_fma_f32 v53, -v10, v51, 1.0
	v_fmac_f32_e32 v51, v53, v51
	v_mul_f32_e32 v53, v52, v51
	v_fma_f32 v54, -v10, v53, v52
	v_fmac_f32_e32 v53, v54, v51
	v_fma_f32 v10, -v10, v53, v52
	v_div_fmas_f32 v10, v10, v51, v53
	v_div_fixup_f32 v6, v10, v7, v156
	ds_write_b32 v162, v6 offset:28
	s_waitcnt vmcnt(2)
	v_mul_f32_e32 v7, 0xbfb8aa3b, v157
	v_fma_f32 v10, v157, s30, -v7
	v_rndne_f32_e32 v51, v7
	v_fmac_f32_e32 v10, 0xb2a5705f, v157
	v_sub_f32_e32 v7, v7, v51
	v_add_f32_e32 v7, v7, v10
	v_cvt_i32_f32_e32 v51, v51
	v_exp_f32_e32 v7, v7
	v_cmp_nlt_f32_e32 vcc, s31, v157
	v_ldexp_f32 v7, v7, v51
	s_nop 0
	v_cndmask_b32_e32 v7, 0, v7, vcc
	v_cmp_ngt_f32_e32 vcc, s33, v157
	s_nop 1
	v_cndmask_b32_e32 v7, v120, v7, vcc
	v_add_f32_e32 v7, 1.0, v7
	v_div_scale_f32 v10, s[18:19], v7, v7, v157
	v_rcp_f32_e32 v51, v10
	v_div_scale_f32 v52, vcc, v157, v7, v157
	v_fma_f32 v53, -v10, v51, 1.0
	v_fmac_f32_e32 v51, v53, v51
	v_mul_f32_e32 v53, v52, v51
	v_fma_f32 v54, -v10, v53, v52
	v_fmac_f32_e32 v53, v54, v51
	v_fma_f32 v10, -v10, v53, v52
	v_div_fmas_f32 v10, v10, v51, v53
	v_div_fixup_f32 v6, v10, v7, v157
	ds_write_b32 v162, v6 offset:24604
	s_waitcnt vmcnt(1)
	v_mul_f32_e32 v7, 0xbfb8aa3b, v158
	v_fma_f32 v10, v158, s30, -v7
	v_rndne_f32_e32 v51, v7
	v_fmac_f32_e32 v10, 0xb2a5705f, v158
	v_sub_f32_e32 v7, v7, v51
	v_add_f32_e32 v7, v7, v10
	v_cvt_i32_f32_e32 v51, v51
	v_exp_f32_e32 v7, v7
	v_cmp_nlt_f32_e32 vcc, s31, v158
	v_ldexp_f32 v7, v7, v51
	s_nop 0
	v_cndmask_b32_e32 v7, 0, v7, vcc
	v_cmp_ngt_f32_e32 vcc, s33, v158
	s_nop 1
	v_cndmask_b32_e32 v7, v120, v7, vcc
	v_add_f32_e32 v7, 1.0, v7
	v_div_scale_f32 v10, s[18:19], v7, v7, v158
	v_rcp_f32_e32 v51, v10
	v_div_scale_f32 v52, vcc, v158, v7, v158
	v_fma_f32 v53, -v10, v51, 1.0
	v_fmac_f32_e32 v51, v53, v51
	v_mul_f32_e32 v53, v52, v51
	v_fma_f32 v54, -v10, v53, v52
	v_fmac_f32_e32 v53, v54, v51
	v_fma_f32 v10, -v10, v53, v52
	v_div_fmas_f32 v10, v10, v51, v53
	v_div_fixup_f32 v6, v10, v7, v158
	ds_write_b32 v162, v6 offset:32
	s_waitcnt vmcnt(0)
	v_mul_f32_e32 v7, 0xbfb8aa3b, v159
	v_fma_f32 v10, v159, s30, -v7
	v_rndne_f32_e32 v51, v7
	v_fmac_f32_e32 v10, 0xb2a5705f, v159
	v_sub_f32_e32 v7, v7, v51
	v_add_f32_e32 v7, v7, v10
	v_cvt_i32_f32_e32 v51, v51
	v_exp_f32_e32 v7, v7
	v_cmp_nlt_f32_e32 vcc, s31, v159
	v_ldexp_f32 v7, v7, v51
	s_nop 0
	v_cndmask_b32_e32 v7, 0, v7, vcc
	v_cmp_ngt_f32_e32 vcc, s33, v159
	s_nop 1
	v_cndmask_b32_e32 v7, v120, v7, vcc
	v_add_f32_e32 v7, 1.0, v7
	v_div_scale_f32 v10, s[18:19], v7, v7, v159
	v_rcp_f32_e32 v51, v10
	v_div_scale_f32 v52, vcc, v159, v7, v159
	v_fma_f32 v53, -v10, v51, 1.0
	v_fmac_f32_e32 v51, v53, v51
	v_mul_f32_e32 v53, v52, v51
	v_fma_f32 v54, -v10, v53, v52
	v_fmac_f32_e32 v53, v54, v51
	v_fma_f32 v10, -v10, v53, v52
	v_div_fmas_f32 v10, v10, v51, v53
	v_div_fixup_f32 v6, v10, v7, v159
	ds_write_b32 v162, v6 offset:24608

.LBB0_364:
	v_mov_b64_e32 v[100:101], 0
	v_mov_b64_e32 v[102:103], 0
	v_mov_b64_e32 v[104:105], 0
	v_mov_b64_e32 v[106:107], 0
	v_mov_b64_e32 v[108:109], 0
	v_mov_b64_e32 v[110:111], 0
	v_mov_b64_e32 v[112:113], 0
	v_mov_b64_e32 v[114:115], 0
	v_mov_b64_e32 v[116:117], 0
	v_mov_b64_e32 v[118:119], 0
	v_mov_b64_e32 v[124:125], 0
	v_mov_b64_e32 v[126:127], 0
	v_mov_b64_e32 v[136:137], 0
	v_mov_b64_e32 v[138:139], 0
	v_mov_b64_e32 v[140:141], 0
	v_mov_b64_e32 v[142:143], 0
	v_mov_b64_e32 v[144:145], 0
	v_mov_b64_e32 v[146:147], 0
	v_mov_b64_e32 v[148:149], 0
	v_mov_b64_e32 v[150:151], 0
	v_mov_b64_e32 v[152:153], 0
	v_mov_b64_e32 v[154:155], 0
	v_mov_b64_e32 v[156:157], 0
	v_mov_b64_e32 v[158:159], 0
	v_mov_b64_e32 v[160:161], 0
	v_mov_b64_e32 v[162:163], 0
	v_mov_b64_e32 v[164:165], 0
	v_mov_b64_e32 v[166:167], 0
	v_mov_b64_e32 v[168:169], 0
	v_mov_b64_e32 v[170:171], 0
	v_mov_b64_e32 v[172:173], 0
	v_mov_b64_e32 v[174:175], 0
	s_and_saveexec_b64 s[10:11], s[6:7]
	v_mad_u64_u32 v[204:205], s[16:17], v8, v18, 0
	v_lshlrev_b32_e32 v206, 3, v18
	v_mov_b32_e32 v207, 0
	v_lshl_add_u64 v[204:205], v[204:205], 2, v[24:25]
	global_load_dwordx4 v[100:103], v[204:205], off
	v_lshl_add_u64 v[204:205], v[204:205], 0, v[206:207]
	global_load_dwordx4 v[104:107], v[204:205], off
	v_lshl_add_u64 v[204:205], v[204:205], 0, v[206:207]
	global_load_dwordx4 v[108:111], v[204:205], off
	v_lshl_add_u64 v[204:205], v[204:205], 0, v[206:207]
	global_load_dwordx4 v[112:115], v[204:205], off
	v_lshl_add_u64 v[204:205], v[204:205], 0, v[206:207]
	global_load_dwordx4 v[116:119], v[204:205], off
	v_lshl_add_u64 v[204:205], v[204:205], 0, v[206:207]
	global_load_dwordx4 v[124:127], v[204:205], off
	v_lshl_add_u64 v[204:205], v[204:205], 0, v[206:207]
	global_load_dwordx4 v[136:139], v[204:205], off
	v_lshl_add_u64 v[204:205], v[204:205], 0, v[206:207]
	global_load_dwordx4 v[140:143], v[204:205], off
	v_lshl_add_u64 v[204:205], v[204:205], 0, v[206:207]
	global_load_dwordx4 v[144:147], v[204:205], off
	v_lshl_add_u64 v[204:205], v[204:205], 0, v[206:207]
	global_load_dwordx4 v[148:151], v[204:205], off
	v_lshl_add_u64 v[204:205], v[204:205], 0, v[206:207]
	global_load_dwordx4 v[152:155], v[204:205], off
	v_lshl_add_u64 v[204:205], v[204:205], 0, v[206:207]
	global_load_dwordx4 v[156:159], v[204:205], off
	v_lshl_add_u64 v[204:205], v[204:205], 0, v[206:207]
	global_load_dwordx4 v[160:163], v[204:205], off
	v_lshl_add_u64 v[204:205], v[204:205], 0, v[206:207]
	global_load_dwordx4 v[164:167], v[204:205], off
	v_lshl_add_u64 v[204:205], v[204:205], 0, v[206:207]
	global_load_dwordx4 v[168:171], v[204:205], off
	v_lshl_add_u64 v[204:205], v[204:205], 0, v[206:207]
	global_load_dwordx4 v[172:175], v[204:205], off
	v_lshl_add_u64 v[204:205], v[204:205], 0, v[206:207]
	s_and_b64 s[16:17], exec, s[8:9]
	s_mov_b64 exec, s[16:17]
	v_lshlrev_b32_e32 v208, 2, v8
	v_mov_b32_e32 v209, 0
	v_lshl_add_u64 v[208:209], v[20:21], 0, v[208:209]
	global_load_dword v176, v[208:209], off
	global_load_dword v177, v[208:209], off offset:8
	global_load_dword v178, v[208:209], off offset:16
	global_load_dword v179, v[208:209], off offset:24
	global_load_dword v180, v[208:209], off offset:32
	global_load_dword v181, v[208:209], off offset:40
	global_load_dword v182, v[208:209], off offset:48
	global_load_dword v183, v[208:209], off offset:56
	global_load_dword v184, v[208:209], off offset:64
	global_load_dword v185, v[208:209], off offset:72
	global_load_dword v186, v[208:209], off offset:80
	global_load_dword v187, v[208:209], off offset:88
	global_load_dword v200, v[208:209], off offset:96
	global_load_dword v201, v[208:209], off offset:104
	global_load_dword v202, v[208:209], off offset:112
	global_load_dword v203, v[208:209], off offset:120
	s_waitcnt vmcnt(15)
	v_mul_f32_e32 v100, v176, v100
	v_mul_f32_e32 v101, v176, v101
	v_mul_f32_e32 v102, v176, v102
	v_mul_f32_e32 v103, v176, v103
	s_mov_b64 exec, s[10:11]
	v_cvt_pk_bf16_f32 v210, v100, v100
	ds_write_b16 v51, v210 offset:0
	v_cvt_pk_bf16_f32 v211, v101, v101
	ds_write_b16 v51, v211 offset:260
	v_cvt_pk_bf16_f32 v210, v102, v102
	ds_write_b16 v51, v210 offset:520
	v_cvt_pk_bf16_f32 v211, v103, v103
	ds_write_b16 v51, v211 offset:780
	s_waitcnt vmcnt(14)
	s_mov_b64 exec, s[16:17]
	v_mul_f32_e32 v104, v177, v104
	v_mul_f32_e32 v105, v177, v105
	v_mul_f32_e32 v106, v177, v106
	v_mul_f32_e32 v107, v177, v107
	s_mov_b64 exec, s[10:11]
	v_cvt_pk_bf16_f32 v210, v104, v104
	ds_write_b16 v51, v210 offset:4
	v_cvt_pk_bf16_f32 v211, v105, v105
	ds_write_b16 v51, v211 offset:264
	v_cvt_pk_bf16_f32 v210, v106, v106
	ds_write_b16 v51, v210 offset:524
	v_cvt_pk_bf16_f32 v211, v107, v107
	ds_write_b16 v51, v211 offset:784
	s_waitcnt vmcnt(13)
	s_mov_b64 exec, s[16:17]
	v_mul_f32_e32 v108, v178, v108
	v_mul_f32_e32 v109, v178, v109
	v_mul_f32_e32 v110, v178, v110
	v_mul_f32_e32 v111, v178, v111
	s_mov_b64 exec, s[10:11]
	v_cvt_pk_bf16_f32 v210, v108, v108
	ds_write_b16 v51, v210 offset:8
	v_cvt_pk_bf16_f32 v211, v109, v109
	ds_write_b16 v51, v211 offset:268
	v_cvt_pk_bf16_f32 v210, v110, v110
	ds_write_b16 v51, v210 offset:528
	v_cvt_pk_bf16_f32 v211, v111, v111
	ds_write_b16 v51, v211 offset:788
	s_waitcnt vmcnt(12)
	s_mov_b64 exec, s[16:17]
	v_mul_f32_e32 v112, v179, v112
	v_mul_f32_e32 v113, v179, v113
	v_mul_f32_e32 v114, v179, v114
	v_mul_f32_e32 v115, v179, v115
	s_mov_b64 exec, s[10:11]
	v_cvt_pk_bf16_f32 v210, v112, v112
	ds_write_b16 v51, v210 offset:12
	v_cvt_pk_bf16_f32 v211, v113, v113
	ds_write_b16 v51, v211 offset:272
	v_cvt_pk_bf16_f32 v210, v114, v114
	ds_write_b16 v51, v210 offset:532
	v_cvt_pk_bf16_f32 v211, v115, v115
	ds_write_b16 v51, v211 offset:792
	s_waitcnt vmcnt(11)
	s_mov_b64 exec, s[16:17]
	v_mul_f32_e32 v116, v180, v116
	v_mul_f32_e32 v117, v180, v117
	v_mul_f32_e32 v118, v180, v118
	v_mul_f32_e32 v119, v180, v119
	s_mov_b64 exec, s[10:11]
	v_cvt_pk_bf16_f32 v210, v116, v116
	ds_write_b16 v51, v210 offset:16
	v_cvt_pk_bf16_f32 v211, v117, v117
	ds_write_b16 v51, v211 offset:276
	v_cvt_pk_bf16_f32 v210, v118, v118
	ds_write_b16 v51, v210 offset:536
	v_cvt_pk_bf16_f32 v211, v119, v119
	ds_write_b16 v51, v211 offset:796
	s_waitcnt vmcnt(10)
	s_mov_b64 exec, s[16:17]
	v_mul_f32_e32 v124, v181, v124
	v_mul_f32_e32 v125, v181, v125
	v_mul_f32_e32 v126, v181, v126
	v_mul_f32_e32 v127, v181, v127
	s_mov_b64 exec, s[10:11]
	v_cvt_pk_bf16_f32 v210, v124, v124
	ds_write_b16 v51, v210 offset:20
	v_cvt_pk_bf16_f32 v211, v125, v125
	ds_write_b16 v51, v211 offset:280
	v_cvt_pk_bf16_f32 v210, v126, v126
	ds_write_b16 v51, v210 offset:540
	v_cvt_pk_bf16_f32 v211, v127, v127
	ds_write_b16 v51, v211 offset:800
	s_waitcnt vmcnt(9)
	s_mov_b64 exec, s[16:17]
	v_mul_f32_e32 v136, v182, v136
	v_mul_f32_e32 v137, v182, v137
	v_mul_f32_e32 v138, v182, v138
	v_mul_f32_e32 v139, v182, v139
	s_mov_b64 exec, s[10:11]
	v_cvt_pk_bf16_f32 v210, v136, v136
	ds_write_b16 v51, v210 offset:24
	v_cvt_pk_bf16_f32 v211, v137, v137
	ds_write_b16 v51, v211 offset:284
	v_cvt_pk_bf16_f32 v210, v138, v138
	ds_write_b16 v51, v210 offset:544
	v_cvt_pk_bf16_f32 v211, v139, v139
	ds_write_b16 v51, v211 offset:804
	s_waitcnt vmcnt(8)
	s_mov_b64 exec, s[16:17]
	v_mul_f32_e32 v140, v183, v140
	v_mul_f32_e32 v141, v183, v141
	v_mul_f32_e32 v142, v183, v142
	v_mul_f32_e32 v143, v183, v143
	s_mov_b64 exec, s[10:11]
	v_cvt_pk_bf16_f32 v210, v140, v140
	ds_write_b16 v51, v210 offset:28
	v_cvt_pk_bf16_f32 v211, v141, v141
	ds_write_b16 v51, v211 offset:288
	v_cvt_pk_bf16_f32 v210, v142, v142
	ds_write_b16 v51, v210 offset:548
	v_cvt_pk_bf16_f32 v211, v143, v143
	ds_write_b16 v51, v211 offset:808
	s_waitcnt vmcnt(7)
	s_mov_b64 exec, s[16:17]
	v_mul_f32_e32 v144, v184, v144
	v_mul_f32_e32 v145, v184, v145
	v_mul_f32_e32 v146, v184, v146
	v_mul_f32_e32 v147, v184, v147
	s_mov_b64 exec, s[10:11]
	v_cvt_pk_bf16_f32 v210, v144, v144
	ds_write_b16 v51, v210 offset:32
	v_cvt_pk_bf16_f32 v211, v145, v145
	ds_write_b16 v51, v211 offset:292
	v_cvt_pk_bf16_f32 v210, v146, v146
	ds_write_b16 v51, v210 offset:552
	v_cvt_pk_bf16_f32 v211, v147, v147
	ds_write_b16 v51, v211 offset:812
	s_waitcnt vmcnt(6)
	s_mov_b64 exec, s[16:17]
	v_mul_f32_e32 v148, v185, v148
	v_mul_f32_e32 v149, v185, v149
	v_mul_f32_e32 v150, v185, v150
	v_mul_f32_e32 v151, v185, v151
	s_mov_b64 exec, s[10:11]
	v_cvt_pk_bf16_f32 v210, v148, v148
	ds_write_b16 v51, v210 offset:36
	v_cvt_pk_bf16_f32 v211, v149, v149
	ds_write_b16 v51, v211 offset:296
	v_cvt_pk_bf16_f32 v210, v150, v150
	ds_write_b16 v51, v210 offset:556
	v_cvt_pk_bf16_f32 v211, v151, v151
	ds_write_b16 v51, v211 offset:816
	s_waitcnt vmcnt(5)
	s_mov_b64 exec, s[16:17]
	v_mul_f32_e32 v152, v186, v152
	v_mul_f32_e32 v153, v186, v153
	v_mul_f32_e32 v154, v186, v154
	v_mul_f32_e32 v155, v186, v155
	s_mov_b64 exec, s[10:11]
	v_cvt_pk_bf16_f32 v210, v152, v152
	ds_write_b16 v51, v210 offset:40
	v_cvt_pk_bf16_f32 v211, v153, v153
	ds_write_b16 v51, v211 offset:300
	v_cvt_pk_bf16_f32 v210, v154, v154
	ds_write_b16 v51, v210 offset:560
	v_cvt_pk_bf16_f32 v211, v155, v155
	ds_write_b16 v51, v211 offset:820
	s_waitcnt vmcnt(4)
	s_mov_b64 exec, s[16:17]
	v_mul_f32_e32 v156, v187, v156
	v_mul_f32_e32 v157, v187, v157
	v_mul_f32_e32 v158, v187, v158
	v_mul_f32_e32 v159, v187, v159
	s_mov_b64 exec, s[10:11]
	v_cvt_pk_bf16_f32 v210, v156, v156
	ds_write_b16 v51, v210 offset:44
	v_cvt_pk_bf16_f32 v211, v157, v157
	ds_write_b16 v51, v211 offset:304
	v_cvt_pk_bf16_f32 v210, v158, v158
	ds_write_b16 v51, v210 offset:564
	v_cvt_pk_bf16_f32 v211, v159, v159
	ds_write_b16 v51, v211 offset:824
	s_waitcnt vmcnt(3)
	s_mov_b64 exec, s[16:17]
	v_mul_f32_e32 v160, v200, v160
	v_mul_f32_e32 v161, v200, v161
	v_mul_f32_e32 v162, v200, v162
	v_mul_f32_e32 v163, v200, v163
	s_mov_b64 exec, s[10:11]
	v_cvt_pk_bf16_f32 v210, v160, v160
	ds_write_b16 v51, v210 offset:48
	v_cvt_pk_bf16_f32 v211, v161, v161
	ds_write_b16 v51, v211 offset:308
	v_cvt_pk_bf16_f32 v210, v162, v162
	ds_write_b16 v51, v210 offset:568
	v_cvt_pk_bf16_f32 v211, v163, v163
	ds_write_b16 v51, v211 offset:828
	s_waitcnt vmcnt(2)
	s_mov_b64 exec, s[16:17]
	v_mul_f32_e32 v164, v201, v164
	v_mul_f32_e32 v165, v201, v165
	v_mul_f32_e32 v166, v201, v166
	v_mul_f32_e32 v167, v201, v167
	s_mov_b64 exec, s[10:11]
	v_cvt_pk_bf16_f32 v210, v164, v164
	ds_write_b16 v51, v210 offset:52
	v_cvt_pk_bf16_f32 v211, v165, v165
	ds_write_b16 v51, v211 offset:312
	v_cvt_pk_bf16_f32 v210, v166, v166
	ds_write_b16 v51, v210 offset:572
	v_cvt_pk_bf16_f32 v211, v167, v167
	ds_write_b16 v51, v211 offset:832
	s_waitcnt vmcnt(1)
	s_mov_b64 exec, s[16:17]
	v_mul_f32_e32 v168, v202, v168
	v_mul_f32_e32 v169, v202, v169
	v_mul_f32_e32 v170, v202, v170
	v_mul_f32_e32 v171, v202, v171
	s_mov_b64 exec, s[10:11]
	v_cvt_pk_bf16_f32 v210, v168, v168
	ds_write_b16 v51, v210 offset:56
	v_cvt_pk_bf16_f32 v211, v169, v169
	ds_write_b16 v51, v211 offset:316
	v_cvt_pk_bf16_f32 v210, v170, v170
	ds_write_b16 v51, v210 offset:576
	v_cvt_pk_bf16_f32 v211, v171, v171
	ds_write_b16 v51, v211 offset:836
	s_waitcnt vmcnt(0)
	s_mov_b64 exec, s[16:17]
	v_mul_f32_e32 v172, v203, v172
	v_mul_f32_e32 v173, v203, v173
	v_mul_f32_e32 v174, v203, v174
	v_mul_f32_e32 v175, v203, v175
	s_mov_b64 exec, s[10:11]
	v_cvt_pk_bf16_f32 v210, v172, v172
	ds_write_b16 v51, v210 offset:60
	v_cvt_pk_bf16_f32 v211, v173, v173
	ds_write_b16 v51, v211 offset:320
	v_cvt_pk_bf16_f32 v210, v174, v174
	ds_write_b16 v51, v210 offset:580
	v_cvt_pk_bf16_f32 v211, v175, v175
	ds_write_b16 v51, v211 offset:840
	s_mov_b32 s24, 32
	v_add_u32_e32 v51, 64, v51
	v_lshl_add_u64 v[26:27], v[26:27], 0, 64
	v_lshl_add_u64 v[26:27], v[26:27], 0, 64
	s_branch .LBB0_298

.LBB0_656:
	v_mov_b64_e32 v[100:101], 0
	v_mov_b64_e32 v[102:103], 0
	v_mov_b64_e32 v[104:105], 0
	v_mov_b64_e32 v[106:107], 0
	v_mov_b64_e32 v[108:109], 0
	v_mov_b64_e32 v[110:111], 0
	v_mov_b64_e32 v[112:113], 0
	v_mov_b64_e32 v[114:115], 0
	v_mov_b64_e32 v[116:117], 0
	v_mov_b64_e32 v[118:119], 0
	v_mov_b64_e32 v[120:121], 0
	v_mov_b64_e32 v[122:123], 0
	v_mov_b64_e32 v[124:125], 0
	v_mov_b64_e32 v[126:127], 0
	v_mov_b64_e32 v[136:137], 0
	v_mov_b64_e32 v[138:139], 0
	v_mov_b64_e32 v[140:141], 0
	v_mov_b64_e32 v[142:143], 0
	v_mov_b64_e32 v[144:145], 0
	v_mov_b64_e32 v[146:147], 0
	v_mov_b64_e32 v[148:149], 0
	v_mov_b64_e32 v[150:151], 0
	v_mov_b64_e32 v[152:153], 0
	v_mov_b64_e32 v[154:155], 0
	v_mov_b64_e32 v[156:157], 0
	v_mov_b64_e32 v[158:159], 0
	v_mov_b64_e32 v[160:161], 0
	v_mov_b64_e32 v[162:163], 0
	v_mov_b64_e32 v[164:165], 0
	v_mov_b64_e32 v[166:167], 0
	v_mov_b64_e32 v[168:169], 0
	v_mov_b64_e32 v[170:171], 0
	s_and_saveexec_b64 s[10:11], s[6:7]
	v_mad_u64_u32 v[200:201], s[16:17], v8, v18, 0
	v_lshlrev_b32_e32 v202, 3, v18
	v_mov_b32_e32 v203, 0
	v_lshl_add_u64 v[200:201], v[200:201], 2, v[24:25]
	global_load_dwordx4 v[100:103], v[200:201], off
	v_lshl_add_u64 v[200:201], v[200:201], 0, v[202:203]
	global_load_dwordx4 v[104:107], v[200:201], off
	v_lshl_add_u64 v[200:201], v[200:201], 0, v[202:203]
	global_load_dwordx4 v[108:111], v[200:201], off
	v_lshl_add_u64 v[200:201], v[200:201], 0, v[202:203]
	global_load_dwordx4 v[112:115], v[200:201], off
	v_lshl_add_u64 v[200:201], v[200:201], 0, v[202:203]
	global_load_dwordx4 v[116:119], v[200:201], off
	v_lshl_add_u64 v[200:201], v[200:201], 0, v[202:203]
	global_load_dwordx4 v[120:123], v[200:201], off
	v_lshl_add_u64 v[200:201], v[200:201], 0, v[202:203]
	global_load_dwordx4 v[124:127], v[200:201], off
	v_lshl_add_u64 v[200:201], v[200:201], 0, v[202:203]
	global_load_dwordx4 v[136:139], v[200:201], off
	v_lshl_add_u64 v[200:201], v[200:201], 0, v[202:203]
	global_load_dwordx4 v[140:143], v[200:201], off
	v_lshl_add_u64 v[200:201], v[200:201], 0, v[202:203]
	global_load_dwordx4 v[144:147], v[200:201], off
	v_lshl_add_u64 v[200:201], v[200:201], 0, v[202:203]
	global_load_dwordx4 v[148:151], v[200:201], off
	v_lshl_add_u64 v[200:201], v[200:201], 0, v[202:203]
	global_load_dwordx4 v[152:155], v[200:201], off
	v_lshl_add_u64 v[200:201], v[200:201], 0, v[202:203]
	global_load_dwordx4 v[156:159], v[200:201], off
	v_lshl_add_u64 v[200:201], v[200:201], 0, v[202:203]
	global_load_dwordx4 v[160:163], v[200:201], off
	v_lshl_add_u64 v[200:201], v[200:201], 0, v[202:203]
	global_load_dwordx4 v[164:167], v[200:201], off
	v_lshl_add_u64 v[200:201], v[200:201], 0, v[202:203]
	global_load_dwordx4 v[168:171], v[200:201], off
	v_lshl_add_u64 v[200:201], v[200:201], 0, v[202:203]
	s_and_b64 s[16:17], exec, s[8:9]
	s_mov_b64 exec, s[16:17]
	v_lshlrev_b32_e32 v204, 2, v8
	v_mov_b32_e32 v205, 0
	v_lshl_add_u64 v[204:205], v[20:21], 0, v[204:205]
	global_load_dword v172, v[204:205], off
	global_load_dword v173, v[204:205], off offset:8
	global_load_dword v174, v[204:205], off offset:16
	global_load_dword v175, v[204:205], off offset:24
	global_load_dword v176, v[204:205], off offset:32
	global_load_dword v177, v[204:205], off offset:40
	global_load_dword v178, v[204:205], off offset:48
	global_load_dword v179, v[204:205], off offset:56
	global_load_dword v180, v[204:205], off offset:64
	global_load_dword v181, v[204:205], off offset:72
	global_load_dword v182, v[204:205], off offset:80
	global_load_dword v183, v[204:205], off offset:88
	global_load_dword v184, v[204:205], off offset:96
	global_load_dword v185, v[204:205], off offset:104
	global_load_dword v186, v[204:205], off offset:112
	global_load_dword v187, v[204:205], off offset:120
	s_waitcnt vmcnt(15)
	v_mul_f32_e32 v100, v172, v100
	v_mul_f32_e32 v101, v172, v101
	v_mul_f32_e32 v102, v172, v102
	v_mul_f32_e32 v103, v172, v103
	s_mov_b64 exec, s[10:11]
	v_cvt_pk_bf16_f32 v206, v100, v100
	ds_write_b16 v51, v206 offset:0
	v_cvt_pk_bf16_f32 v207, v101, v101
	ds_write_b16 v51, v207 offset:260
	v_cvt_pk_bf16_f32 v206, v102, v102
	ds_write_b16 v51, v206 offset:520
	v_cvt_pk_bf16_f32 v207, v103, v103
	ds_write_b16 v51, v207 offset:780
	s_waitcnt vmcnt(14)
	s_mov_b64 exec, s[16:17]
	v_mul_f32_e32 v104, v173, v104
	v_mul_f32_e32 v105, v173, v105
	v_mul_f32_e32 v106, v173, v106
	v_mul_f32_e32 v107, v173, v107
	s_mov_b64 exec, s[10:11]
	v_cvt_pk_bf16_f32 v206, v104, v104
	ds_write_b16 v51, v206 offset:4
	v_cvt_pk_bf16_f32 v207, v105, v105
	ds_write_b16 v51, v207 offset:264
	v_cvt_pk_bf16_f32 v206, v106, v106
	ds_write_b16 v51, v206 offset:524
	v_cvt_pk_bf16_f32 v207, v107, v107
	ds_write_b16 v51, v207 offset:784
	s_waitcnt vmcnt(13)
	s_mov_b64 exec, s[16:17]
	v_mul_f32_e32 v108, v174, v108
	v_mul_f32_e32 v109, v174, v109
	v_mul_f32_e32 v110, v174, v110
	v_mul_f32_e32 v111, v174, v111
	s_mov_b64 exec, s[10:11]
	v_cvt_pk_bf16_f32 v206, v108, v108
	ds_write_b16 v51, v206 offset:8
	v_cvt_pk_bf16_f32 v207, v109, v109
	ds_write_b16 v51, v207 offset:268
	v_cvt_pk_bf16_f32 v206, v110, v110
	ds_write_b16 v51, v206 offset:528
	v_cvt_pk_bf16_f32 v207, v111, v111
	ds_write_b16 v51, v207 offset:788
	s_waitcnt vmcnt(12)
	s_mov_b64 exec, s[16:17]
	v_mul_f32_e32 v112, v175, v112
	v_mul_f32_e32 v113, v175, v113
	v_mul_f32_e32 v114, v175, v114
	v_mul_f32_e32 v115, v175, v115
	s_mov_b64 exec, s[10:11]
	v_cvt_pk_bf16_f32 v206, v112, v112
	ds_write_b16 v51, v206 offset:12
	v_cvt_pk_bf16_f32 v207, v113, v113
	ds_write_b16 v51, v207 offset:272
	v_cvt_pk_bf16_f32 v206, v114, v114
	ds_write_b16 v51, v206 offset:532
	v_cvt_pk_bf16_f32 v207, v115, v115
	ds_write_b16 v51, v207 offset:792
	s_waitcnt vmcnt(11)
	s_mov_b64 exec, s[16:17]
	v_mul_f32_e32 v116, v176, v116
	v_mul_f32_e32 v117, v176, v117
	v_mul_f32_e32 v118, v176, v118
	v_mul_f32_e32 v119, v176, v119
	s_mov_b64 exec, s[10:11]
	v_cvt_pk_bf16_f32 v206, v116, v116
	ds_write_b16 v51, v206 offset:16
	v_cvt_pk_bf16_f32 v207, v117, v117
	ds_write_b16 v51, v207 offset:276
	v_cvt_pk_bf16_f32 v206, v118, v118
	ds_write_b16 v51, v206 offset:536
	v_cvt_pk_bf16_f32 v207, v119, v119
	ds_write_b16 v51, v207 offset:796
	s_waitcnt vmcnt(10)
	s_mov_b64 exec, s[16:17]
	v_mul_f32_e32 v120, v177, v120
	v_mul_f32_e32 v121, v177, v121
	v_mul_f32_e32 v122, v177, v122
	v_mul_f32_e32 v123, v177, v123
	s_mov_b64 exec, s[10:11]
	v_cvt_pk_bf16_f32 v206, v120, v120
	ds_write_b16 v51, v206 offset:20
	v_cvt_pk_bf16_f32 v207, v121, v121
	ds_write_b16 v51, v207 offset:280
	v_cvt_pk_bf16_f32 v206, v122, v122
	ds_write_b16 v51, v206 offset:540
	v_cvt_pk_bf16_f32 v207, v123, v123
	ds_write_b16 v51, v207 offset:800
	s_waitcnt vmcnt(9)
	s_mov_b64 exec, s[16:17]
	v_mul_f32_e32 v124, v178, v124
	v_mul_f32_e32 v125, v178, v125
	v_mul_f32_e32 v126, v178, v126
	v_mul_f32_e32 v127, v178, v127
	s_mov_b64 exec, s[10:11]
	v_cvt_pk_bf16_f32 v206, v124, v124
	ds_write_b16 v51, v206 offset:24
	v_cvt_pk_bf16_f32 v207, v125, v125
	ds_write_b16 v51, v207 offset:284
	v_cvt_pk_bf16_f32 v206, v126, v126
	ds_write_b16 v51, v206 offset:544
	v_cvt_pk_bf16_f32 v207, v127, v127
	ds_write_b16 v51, v207 offset:804
	s_waitcnt vmcnt(8)
	s_mov_b64 exec, s[16:17]
	v_mul_f32_e32 v136, v179, v136
	v_mul_f32_e32 v137, v179, v137
	v_mul_f32_e32 v138, v179, v138
	v_mul_f32_e32 v139, v179, v139
	s_mov_b64 exec, s[10:11]
	v_cvt_pk_bf16_f32 v206, v136, v136
	ds_write_b16 v51, v206 offset:28
	v_cvt_pk_bf16_f32 v207, v137, v137
	ds_write_b16 v51, v207 offset:288
	v_cvt_pk_bf16_f32 v206, v138, v138
	ds_write_b16 v51, v206 offset:548
	v_cvt_pk_bf16_f32 v207, v139, v139
	ds_write_b16 v51, v207 offset:808
	s_waitcnt vmcnt(7)
	s_mov_b64 exec, s[16:17]
	v_mul_f32_e32 v140, v180, v140
	v_mul_f32_e32 v141, v180, v141
	v_mul_f32_e32 v142, v180, v142
	v_mul_f32_e32 v143, v180, v143
	s_mov_b64 exec, s[10:11]
	v_cvt_pk_bf16_f32 v206, v140, v140
	ds_write_b16 v51, v206 offset:32
	v_cvt_pk_bf16_f32 v207, v141, v141
	ds_write_b16 v51, v207 offset:292
	v_cvt_pk_bf16_f32 v206, v142, v142
	ds_write_b16 v51, v206 offset:552
	v_cvt_pk_bf16_f32 v207, v143, v143
	ds_write_b16 v51, v207 offset:812
	s_waitcnt vmcnt(6)
	s_mov_b64 exec, s[16:17]
	v_mul_f32_e32 v144, v181, v144
	v_mul_f32_e32 v145, v181, v145
	v_mul_f32_e32 v146, v181, v146
	v_mul_f32_e32 v147, v181, v147
	s_mov_b64 exec, s[10:11]
	v_cvt_pk_bf16_f32 v206, v144, v144
	ds_write_b16 v51, v206 offset:36
	v_cvt_pk_bf16_f32 v207, v145, v145
	ds_write_b16 v51, v207 offset:296
	v_cvt_pk_bf16_f32 v206, v146, v146
	ds_write_b16 v51, v206 offset:556
	v_cvt_pk_bf16_f32 v207, v147, v147
	ds_write_b16 v51, v207 offset:816
	s_waitcnt vmcnt(5)
	s_mov_b64 exec, s[16:17]
	v_mul_f32_e32 v148, v182, v148
	v_mul_f32_e32 v149, v182, v149
	v_mul_f32_e32 v150, v182, v150
	v_mul_f32_e32 v151, v182, v151
	s_mov_b64 exec, s[10:11]
	v_cvt_pk_bf16_f32 v206, v148, v148
	ds_write_b16 v51, v206 offset:40
	v_cvt_pk_bf16_f32 v207, v149, v149
	ds_write_b16 v51, v207 offset:300
	v_cvt_pk_bf16_f32 v206, v150, v150
	ds_write_b16 v51, v206 offset:560
	v_cvt_pk_bf16_f32 v207, v151, v151
	ds_write_b16 v51, v207 offset:820
	s_waitcnt vmcnt(4)
	s_mov_b64 exec, s[16:17]
	v_mul_f32_e32 v152, v183, v152
	v_mul_f32_e32 v153, v183, v153
	v_mul_f32_e32 v154, v183, v154
	v_mul_f32_e32 v155, v183, v155
	s_mov_b64 exec, s[10:11]
	v_cvt_pk_bf16_f32 v206, v152, v152
	ds_write_b16 v51, v206 offset:44
	v_cvt_pk_bf16_f32 v207, v153, v153
	ds_write_b16 v51, v207 offset:304
	v_cvt_pk_bf16_f32 v206, v154, v154
	ds_write_b16 v51, v206 offset:564
	v_cvt_pk_bf16_f32 v207, v155, v155
	ds_write_b16 v51, v207 offset:824
	s_waitcnt vmcnt(3)
	s_mov_b64 exec, s[16:17]
	v_mul_f32_e32 v156, v184, v156
	v_mul_f32_e32 v157, v184, v157
	v_mul_f32_e32 v158, v184, v158
	v_mul_f32_e32 v159, v184, v159
	s_mov_b64 exec, s[10:11]
	v_cvt_pk_bf16_f32 v206, v156, v156
	ds_write_b16 v51, v206 offset:48
	v_cvt_pk_bf16_f32 v207, v157, v157
	ds_write_b16 v51, v207 offset:308
	v_cvt_pk_bf16_f32 v206, v158, v158
	ds_write_b16 v51, v206 offset:568
	v_cvt_pk_bf16_f32 v207, v159, v159
	ds_write_b16 v51, v207 offset:828
	s_waitcnt vmcnt(2)
	s_mov_b64 exec, s[16:17]
	v_mul_f32_e32 v160, v185, v160
	v_mul_f32_e32 v161, v185, v161
	v_mul_f32_e32 v162, v185, v162
	v_mul_f32_e32 v163, v185, v163
	s_mov_b64 exec, s[10:11]
	v_cvt_pk_bf16_f32 v206, v160, v160
	ds_write_b16 v51, v206 offset:52
	v_cvt_pk_bf16_f32 v207, v161, v161
	ds_write_b16 v51, v207 offset:312
	v_cvt_pk_bf16_f32 v206, v162, v162
	ds_write_b16 v51, v206 offset:572
	v_cvt_pk_bf16_f32 v207, v163, v163
	ds_write_b16 v51, v207 offset:832
	s_waitcnt vmcnt(1)
	s_mov_b64 exec, s[16:17]
	v_mul_f32_e32 v164, v186, v164
	v_mul_f32_e32 v165, v186, v165
	v_mul_f32_e32 v166, v186, v166
	v_mul_f32_e32 v167, v186, v167
	s_mov_b64 exec, s[10:11]
	v_cvt_pk_bf16_f32 v206, v164, v164
	ds_write_b16 v51, v206 offset:56
	v_cvt_pk_bf16_f32 v207, v165, v165
	ds_write_b16 v51, v207 offset:316
	v_cvt_pk_bf16_f32 v206, v166, v166
	ds_write_b16 v51, v206 offset:576
	v_cvt_pk_bf16_f32 v207, v167, v167
	ds_write_b16 v51, v207 offset:836
	s_waitcnt vmcnt(0)
	s_mov_b64 exec, s[16:17]
	v_mul_f32_e32 v168, v187, v168
	v_mul_f32_e32 v169, v187, v169
	v_mul_f32_e32 v170, v187, v170
	v_mul_f32_e32 v171, v187, v171
	s_mov_b64 exec, s[10:11]
	v_cvt_pk_bf16_f32 v206, v168, v168
	ds_write_b16 v51, v206 offset:60
	v_cvt_pk_bf16_f32 v207, v169, v169
	ds_write_b16 v51, v207 offset:320
	v_cvt_pk_bf16_f32 v206, v170, v170
	ds_write_b16 v51, v206 offset:580
	v_cvt_pk_bf16_f32 v207, v171, v171
	ds_write_b16 v51, v207 offset:840
	s_mov_b32 s24, 32
	v_add_u32_e32 v51, 64, v51
	v_lshl_add_u64 v[26:27], v[26:27], 0, 64
	v_lshl_add_u64 v[26:27], v[26:27], 0, 64
	s_branch .LBB0_590

.LBB0_842:
	v_mov_b64_e32 v[100:101], 0
	v_mov_b64_e32 v[102:103], 0
	v_mov_b64_e32 v[104:105], 0
	v_mov_b64_e32 v[106:107], 0
	v_mov_b64_e32 v[108:109], 0
	v_mov_b64_e32 v[110:111], 0
	v_mov_b64_e32 v[112:113], 0
	v_mov_b64_e32 v[114:115], 0
	v_mov_b64_e32 v[116:117], 0
	v_mov_b64_e32 v[118:119], 0
	v_mov_b64_e32 v[120:121], 0
	v_mov_b64_e32 v[122:123], 0
	v_mov_b64_e32 v[124:125], 0
	v_mov_b64_e32 v[126:127], 0
	v_mov_b64_e32 v[136:137], 0
	v_mov_b64_e32 v[138:139], 0
	v_mov_b64_e32 v[140:141], 0
	v_mov_b64_e32 v[142:143], 0
	v_mov_b64_e32 v[144:145], 0
	v_mov_b64_e32 v[146:147], 0
	v_mov_b64_e32 v[148:149], 0
	v_mov_b64_e32 v[150:151], 0
	v_mov_b64_e32 v[152:153], 0
	v_mov_b64_e32 v[154:155], 0
	v_mov_b64_e32 v[156:157], 0
	v_mov_b64_e32 v[158:159], 0
	v_mov_b64_e32 v[160:161], 0
	v_mov_b64_e32 v[162:163], 0
	v_mov_b64_e32 v[164:165], 0
	v_mov_b64_e32 v[166:167], 0
	v_mov_b64_e32 v[168:169], 0
	v_mov_b64_e32 v[170:171], 0
	s_and_saveexec_b64 s[10:11], s[6:7]
	v_mad_u64_u32 v[200:201], s[12:13], v8, v18, 0
	v_lshlrev_b32_e32 v202, 3, v18
	v_mov_b32_e32 v203, 0
	v_lshl_add_u64 v[200:201], v[200:201], 2, v[24:25]
	global_load_dwordx4 v[100:103], v[200:201], off
	v_lshl_add_u64 v[200:201], v[200:201], 0, v[202:203]
	global_load_dwordx4 v[104:107], v[200:201], off
	v_lshl_add_u64 v[200:201], v[200:201], 0, v[202:203]
	global_load_dwordx4 v[108:111], v[200:201], off
	v_lshl_add_u64 v[200:201], v[200:201], 0, v[202:203]
	global_load_dwordx4 v[112:115], v[200:201], off
	v_lshl_add_u64 v[200:201], v[200:201], 0, v[202:203]
	global_load_dwordx4 v[116:119], v[200:201], off
	v_lshl_add_u64 v[200:201], v[200:201], 0, v[202:203]
	global_load_dwordx4 v[120:123], v[200:201], off
	v_lshl_add_u64 v[200:201], v[200:201], 0, v[202:203]
	global_load_dwordx4 v[124:127], v[200:201], off
	v_lshl_add_u64 v[200:201], v[200:201], 0, v[202:203]
	global_load_dwordx4 v[136:139], v[200:201], off
	v_lshl_add_u64 v[200:201], v[200:201], 0, v[202:203]
	global_load_dwordx4 v[140:143], v[200:201], off
	v_lshl_add_u64 v[200:201], v[200:201], 0, v[202:203]
	global_load_dwordx4 v[144:147], v[200:201], off
	v_lshl_add_u64 v[200:201], v[200:201], 0, v[202:203]
	global_load_dwordx4 v[148:151], v[200:201], off
	v_lshl_add_u64 v[200:201], v[200:201], 0, v[202:203]
	global_load_dwordx4 v[152:155], v[200:201], off
	v_lshl_add_u64 v[200:201], v[200:201], 0, v[202:203]
	global_load_dwordx4 v[156:159], v[200:201], off
	v_lshl_add_u64 v[200:201], v[200:201], 0, v[202:203]
	global_load_dwordx4 v[160:163], v[200:201], off
	v_lshl_add_u64 v[200:201], v[200:201], 0, v[202:203]
	global_load_dwordx4 v[164:167], v[200:201], off
	v_lshl_add_u64 v[200:201], v[200:201], 0, v[202:203]
	global_load_dwordx4 v[168:171], v[200:201], off
	v_lshl_add_u64 v[200:201], v[200:201], 0, v[202:203]
	s_and_b64 s[12:13], exec, s[8:9]
	s_mov_b64 exec, s[12:13]
	v_lshlrev_b32_e32 v204, 2, v8
	v_mov_b32_e32 v205, 0
	v_lshl_add_u64 v[204:205], v[20:21], 0, v[204:205]
	global_load_dword v172, v[204:205], off
	global_load_dword v173, v[204:205], off offset:8
	global_load_dword v174, v[204:205], off offset:16
	global_load_dword v175, v[204:205], off offset:24
	global_load_dword v176, v[204:205], off offset:32
	global_load_dword v177, v[204:205], off offset:40
	global_load_dword v178, v[204:205], off offset:48
	global_load_dword v179, v[204:205], off offset:56
	global_load_dword v180, v[204:205], off offset:64
	global_load_dword v181, v[204:205], off offset:72
	global_load_dword v182, v[204:205], off offset:80
	global_load_dword v183, v[204:205], off offset:88
	global_load_dword v184, v[204:205], off offset:96
	global_load_dword v185, v[204:205], off offset:104
	global_load_dword v186, v[204:205], off offset:112
	global_load_dword v187, v[204:205], off offset:120
	s_waitcnt vmcnt(15)
	v_mul_f32_e32 v100, v172, v100
	v_mul_f32_e32 v101, v172, v101
	v_mul_f32_e32 v102, v172, v102
	v_mul_f32_e32 v103, v172, v103
	s_mov_b64 exec, s[10:11]
	v_cvt_pk_bf16_f32 v206, v100, v100
	ds_write_b16 v51, v206 offset:0
	v_cvt_pk_bf16_f32 v207, v101, v101
	ds_write_b16 v51, v207 offset:260
	v_cvt_pk_bf16_f32 v206, v102, v102
	ds_write_b16 v51, v206 offset:520
	v_cvt_pk_bf16_f32 v207, v103, v103
	ds_write_b16 v51, v207 offset:780
	s_waitcnt vmcnt(14)
	s_mov_b64 exec, s[12:13]
	v_mul_f32_e32 v104, v173, v104
	v_mul_f32_e32 v105, v173, v105
	v_mul_f32_e32 v106, v173, v106
	v_mul_f32_e32 v107, v173, v107
	s_mov_b64 exec, s[10:11]
	v_cvt_pk_bf16_f32 v206, v104, v104
	ds_write_b16 v51, v206 offset:4
	v_cvt_pk_bf16_f32 v207, v105, v105
	ds_write_b16 v51, v207 offset:264
	v_cvt_pk_bf16_f32 v206, v106, v106
	ds_write_b16 v51, v206 offset:524
	v_cvt_pk_bf16_f32 v207, v107, v107
	ds_write_b16 v51, v207 offset:784
	s_waitcnt vmcnt(13)
	s_mov_b64 exec, s[12:13]
	v_mul_f32_e32 v108, v174, v108
	v_mul_f32_e32 v109, v174, v109
	v_mul_f32_e32 v110, v174, v110
	v_mul_f32_e32 v111, v174, v111
	s_mov_b64 exec, s[10:11]
	v_cvt_pk_bf16_f32 v206, v108, v108
	ds_write_b16 v51, v206 offset:8
	v_cvt_pk_bf16_f32 v207, v109, v109
	ds_write_b16 v51, v207 offset:268
	v_cvt_pk_bf16_f32 v206, v110, v110
	ds_write_b16 v51, v206 offset:528
	v_cvt_pk_bf16_f32 v207, v111, v111
	ds_write_b16 v51, v207 offset:788
	s_waitcnt vmcnt(12)
	s_mov_b64 exec, s[12:13]
	v_mul_f32_e32 v112, v175, v112
	v_mul_f32_e32 v113, v175, v113
	v_mul_f32_e32 v114, v175, v114
	v_mul_f32_e32 v115, v175, v115
	s_mov_b64 exec, s[10:11]
	v_cvt_pk_bf16_f32 v206, v112, v112
	ds_write_b16 v51, v206 offset:12
	v_cvt_pk_bf16_f32 v207, v113, v113
	ds_write_b16 v51, v207 offset:272
	v_cvt_pk_bf16_f32 v206, v114, v114
	ds_write_b16 v51, v206 offset:532
	v_cvt_pk_bf16_f32 v207, v115, v115
	ds_write_b16 v51, v207 offset:792
	s_waitcnt vmcnt(11)
	s_mov_b64 exec, s[12:13]
	v_mul_f32_e32 v116, v176, v116
	v_mul_f32_e32 v117, v176, v117
	v_mul_f32_e32 v118, v176, v118
	v_mul_f32_e32 v119, v176, v119
	s_mov_b64 exec, s[10:11]
	v_cvt_pk_bf16_f32 v206, v116, v116
	ds_write_b16 v51, v206 offset:16
	v_cvt_pk_bf16_f32 v207, v117, v117
	ds_write_b16 v51, v207 offset:276
	v_cvt_pk_bf16_f32 v206, v118, v118
	ds_write_b16 v51, v206 offset:536
	v_cvt_pk_bf16_f32 v207, v119, v119
	ds_write_b16 v51, v207 offset:796
	s_waitcnt vmcnt(10)
	s_mov_b64 exec, s[12:13]
	v_mul_f32_e32 v120, v177, v120
	v_mul_f32_e32 v121, v177, v121
	v_mul_f32_e32 v122, v177, v122
	v_mul_f32_e32 v123, v177, v123
	s_mov_b64 exec, s[10:11]
	v_cvt_pk_bf16_f32 v206, v120, v120
	ds_write_b16 v51, v206 offset:20
	v_cvt_pk_bf16_f32 v207, v121, v121
	ds_write_b16 v51, v207 offset:280
	v_cvt_pk_bf16_f32 v206, v122, v122
	ds_write_b16 v51, v206 offset:540
	v_cvt_pk_bf16_f32 v207, v123, v123
	ds_write_b16 v51, v207 offset:800
	s_waitcnt vmcnt(9)
	s_mov_b64 exec, s[12:13]
	v_mul_f32_e32 v124, v178, v124
	v_mul_f32_e32 v125, v178, v125
	v_mul_f32_e32 v126, v178, v126
	v_mul_f32_e32 v127, v178, v127
	s_mov_b64 exec, s[10:11]
	v_cvt_pk_bf16_f32 v206, v124, v124
	ds_write_b16 v51, v206 offset:24
	v_cvt_pk_bf16_f32 v207, v125, v125
	ds_write_b16 v51, v207 offset:284
	v_cvt_pk_bf16_f32 v206, v126, v126
	ds_write_b16 v51, v206 offset:544
	v_cvt_pk_bf16_f32 v207, v127, v127
	ds_write_b16 v51, v207 offset:804
	s_waitcnt vmcnt(8)
	s_mov_b64 exec, s[12:13]
	v_mul_f32_e32 v136, v179, v136
	v_mul_f32_e32 v137, v179, v137
	v_mul_f32_e32 v138, v179, v138
	v_mul_f32_e32 v139, v179, v139
	s_mov_b64 exec, s[10:11]
	v_cvt_pk_bf16_f32 v206, v136, v136
	ds_write_b16 v51, v206 offset:28
	v_cvt_pk_bf16_f32 v207, v137, v137
	ds_write_b16 v51, v207 offset:288
	v_cvt_pk_bf16_f32 v206, v138, v138
	ds_write_b16 v51, v206 offset:548
	v_cvt_pk_bf16_f32 v207, v139, v139
	ds_write_b16 v51, v207 offset:808
	s_waitcnt vmcnt(7)
	s_mov_b64 exec, s[12:13]
	v_mul_f32_e32 v140, v180, v140
	v_mul_f32_e32 v141, v180, v141
	v_mul_f32_e32 v142, v180, v142
	v_mul_f32_e32 v143, v180, v143
	s_mov_b64 exec, s[10:11]
	v_cvt_pk_bf16_f32 v206, v140, v140
	ds_write_b16 v51, v206 offset:32
	v_cvt_pk_bf16_f32 v207, v141, v141
	ds_write_b16 v51, v207 offset:292
	v_cvt_pk_bf16_f32 v206, v142, v142
	ds_write_b16 v51, v206 offset:552
	v_cvt_pk_bf16_f32 v207, v143, v143
	ds_write_b16 v51, v207 offset:812
	s_waitcnt vmcnt(6)
	s_mov_b64 exec, s[12:13]
	v_mul_f32_e32 v144, v181, v144
	v_mul_f32_e32 v145, v181, v145
	v_mul_f32_e32 v146, v181, v146
	v_mul_f32_e32 v147, v181, v147
	s_mov_b64 exec, s[10:11]
	v_cvt_pk_bf16_f32 v206, v144, v144
	ds_write_b16 v51, v206 offset:36
	v_cvt_pk_bf16_f32 v207, v145, v145
	ds_write_b16 v51, v207 offset:296
	v_cvt_pk_bf16_f32 v206, v146, v146
	ds_write_b16 v51, v206 offset:556
	v_cvt_pk_bf16_f32 v207, v147, v147
	ds_write_b16 v51, v207 offset:816
	s_waitcnt vmcnt(5)
	s_mov_b64 exec, s[12:13]
	v_mul_f32_e32 v148, v182, v148
	v_mul_f32_e32 v149, v182, v149
	v_mul_f32_e32 v150, v182, v150
	v_mul_f32_e32 v151, v182, v151
	s_mov_b64 exec, s[10:11]
	v_cvt_pk_bf16_f32 v206, v148, v148
	ds_write_b16 v51, v206 offset:40
	v_cvt_pk_bf16_f32 v207, v149, v149
	ds_write_b16 v51, v207 offset:300
	v_cvt_pk_bf16_f32 v206, v150, v150
	ds_write_b16 v51, v206 offset:560
	v_cvt_pk_bf16_f32 v207, v151, v151
	ds_write_b16 v51, v207 offset:820
	s_waitcnt vmcnt(4)
	s_mov_b64 exec, s[12:13]
	v_mul_f32_e32 v152, v183, v152
	v_mul_f32_e32 v153, v183, v153
	v_mul_f32_e32 v154, v183, v154
	v_mul_f32_e32 v155, v183, v155
	s_mov_b64 exec, s[10:11]
	v_cvt_pk_bf16_f32 v206, v152, v152
	ds_write_b16 v51, v206 offset:44
	v_cvt_pk_bf16_f32 v207, v153, v153
	ds_write_b16 v51, v207 offset:304
	v_cvt_pk_bf16_f32 v206, v154, v154
	ds_write_b16 v51, v206 offset:564
	v_cvt_pk_bf16_f32 v207, v155, v155
	ds_write_b16 v51, v207 offset:824
	s_waitcnt vmcnt(3)
	s_mov_b64 exec, s[12:13]
	v_mul_f32_e32 v156, v184, v156
	v_mul_f32_e32 v157, v184, v157
	v_mul_f32_e32 v158, v184, v158
	v_mul_f32_e32 v159, v184, v159
	s_mov_b64 exec, s[10:11]
	v_cvt_pk_bf16_f32 v206, v156, v156
	ds_write_b16 v51, v206 offset:48
	v_cvt_pk_bf16_f32 v207, v157, v157
	ds_write_b16 v51, v207 offset:308
	v_cvt_pk_bf16_f32 v206, v158, v158
	ds_write_b16 v51, v206 offset:568
	v_cvt_pk_bf16_f32 v207, v159, v159
	ds_write_b16 v51, v207 offset:828
	s_waitcnt vmcnt(2)
	s_mov_b64 exec, s[12:13]
	v_mul_f32_e32 v160, v185, v160
	v_mul_f32_e32 v161, v185, v161
	v_mul_f32_e32 v162, v185, v162
	v_mul_f32_e32 v163, v185, v163
	s_mov_b64 exec, s[10:11]
	v_cvt_pk_bf16_f32 v206, v160, v160
	ds_write_b16 v51, v206 offset:52
	v_cvt_pk_bf16_f32 v207, v161, v161
	ds_write_b16 v51, v207 offset:312
	v_cvt_pk_bf16_f32 v206, v162, v162
	ds_write_b16 v51, v206 offset:572
	v_cvt_pk_bf16_f32 v207, v163, v163
	ds_write_b16 v51, v207 offset:832
	s_waitcnt vmcnt(1)
	s_mov_b64 exec, s[12:13]
	v_mul_f32_e32 v164, v186, v164
	v_mul_f32_e32 v165, v186, v165
	v_mul_f32_e32 v166, v186, v166
	v_mul_f32_e32 v167, v186, v167
	s_mov_b64 exec, s[10:11]
	v_cvt_pk_bf16_f32 v206, v164, v164
	ds_write_b16 v51, v206 offset:56
	v_cvt_pk_bf16_f32 v207, v165, v165
	ds_write_b16 v51, v207 offset:316
	v_cvt_pk_bf16_f32 v206, v166, v166
	ds_write_b16 v51, v206 offset:576
	v_cvt_pk_bf16_f32 v207, v167, v167
	ds_write_b16 v51, v207 offset:836
	s_waitcnt vmcnt(0)
	s_mov_b64 exec, s[12:13]
	v_mul_f32_e32 v168, v187, v168
	v_mul_f32_e32 v169, v187, v169
	v_mul_f32_e32 v170, v187, v170
	v_mul_f32_e32 v171, v187, v171
	s_mov_b64 exec, s[10:11]
	v_cvt_pk_bf16_f32 v206, v168, v168
	ds_write_b16 v51, v206 offset:60
	v_cvt_pk_bf16_f32 v207, v169, v169
	ds_write_b16 v51, v207 offset:320
	v_cvt_pk_bf16_f32 v206, v170, v170
	ds_write_b16 v51, v206 offset:580
	v_cvt_pk_bf16_f32 v207, v171, v171
	ds_write_b16 v51, v207 offset:840
	s_mov_b32 s16, 32
	v_add_u32_e32 v51, 64, v51
	v_lshl_add_u64 v[26:27], v[26:27], 0, 64
	v_lshl_add_u64 v[26:27], v[26:27], 0, 64
	s_branch .LBB0_776

.LBB0_1291:
	v_mov_b64_e32 v[112:113], 0
	v_mov_b64_e32 v[114:115], 0
	v_mov_b64_e32 v[116:117], 0
	v_mov_b64_e32 v[118:119], 0
	v_mov_b64_e32 v[120:121], 0
	v_mov_b64_e32 v[122:123], 0
	v_mov_b64_e32 v[124:125], 0
	v_mov_b64_e32 v[126:127], 0
	v_mov_b64_e32 v[136:137], 0
	v_mov_b64_e32 v[138:139], 0
	v_mov_b64_e32 v[140:141], 0
	v_mov_b64_e32 v[142:143], 0
	v_mov_b64_e32 v[144:145], 0
	v_mov_b64_e32 v[146:147], 0
	v_mov_b64_e32 v[148:149], 0
	v_mov_b64_e32 v[150:151], 0
	v_mov_b64_e32 v[152:153], 0
	v_mov_b64_e32 v[154:155], 0
	v_mov_b64_e32 v[156:157], 0
	v_mov_b64_e32 v[158:159], 0
	v_mov_b64_e32 v[160:161], 0
	v_mov_b64_e32 v[162:163], 0
	v_mov_b64_e32 v[164:165], 0
	v_mov_b64_e32 v[166:167], 0
	v_mov_b64_e32 v[168:169], 0
	v_mov_b64_e32 v[170:171], 0
	v_mov_b64_e32 v[172:173], 0
	v_mov_b64_e32 v[174:175], 0
	v_mov_b64_e32 v[176:177], 0
	v_mov_b64_e32 v[178:179], 0
	v_mov_b64_e32 v[180:181], 0
	v_mov_b64_e32 v[182:183], 0
	s_and_saveexec_b64 s[12:13], s[8:9]
	v_mad_u64_u32 v[244:245], s[16:17], v8, v18, 0
	v_lshlrev_b32_e32 v246, 3, v18
	v_mov_b32_e32 v247, 0
	v_lshl_add_u64 v[244:245], v[244:245], 2, v[24:25]
	global_load_dwordx4 v[112:115], v[244:245], off
	v_lshl_add_u64 v[244:245], v[244:245], 0, v[246:247]
	global_load_dwordx4 v[116:119], v[244:245], off
	v_lshl_add_u64 v[244:245], v[244:245], 0, v[246:247]
	global_load_dwordx4 v[120:123], v[244:245], off
	v_lshl_add_u64 v[244:245], v[244:245], 0, v[246:247]
	global_load_dwordx4 v[124:127], v[244:245], off
	v_lshl_add_u64 v[244:245], v[244:245], 0, v[246:247]
	global_load_dwordx4 v[136:139], v[244:245], off
	v_lshl_add_u64 v[244:245], v[244:245], 0, v[246:247]
	global_load_dwordx4 v[140:143], v[244:245], off
	v_lshl_add_u64 v[244:245], v[244:245], 0, v[246:247]
	global_load_dwordx4 v[144:147], v[244:245], off
	v_lshl_add_u64 v[244:245], v[244:245], 0, v[246:247]
	global_load_dwordx4 v[148:151], v[244:245], off
	v_lshl_add_u64 v[244:245], v[244:245], 0, v[246:247]
	global_load_dwordx4 v[152:155], v[244:245], off
	v_lshl_add_u64 v[244:245], v[244:245], 0, v[246:247]
	global_load_dwordx4 v[156:159], v[244:245], off
	v_lshl_add_u64 v[244:245], v[244:245], 0, v[246:247]
	global_load_dwordx4 v[160:163], v[244:245], off
	v_lshl_add_u64 v[244:245], v[244:245], 0, v[246:247]
	global_load_dwordx4 v[164:167], v[244:245], off
	v_lshl_add_u64 v[244:245], v[244:245], 0, v[246:247]
	global_load_dwordx4 v[168:171], v[244:245], off
	v_lshl_add_u64 v[244:245], v[244:245], 0, v[246:247]
	global_load_dwordx4 v[172:175], v[244:245], off
	v_lshl_add_u64 v[244:245], v[244:245], 0, v[246:247]
	global_load_dwordx4 v[176:179], v[244:245], off
	v_lshl_add_u64 v[244:245], v[244:245], 0, v[246:247]
	global_load_dwordx4 v[180:183], v[244:245], off
	v_lshl_add_u64 v[244:245], v[244:245], 0, v[246:247]
	s_and_b64 s[16:17], exec, s[10:11]
	s_mov_b64 exec, s[16:17]
	v_lshlrev_b32_e32 v248, 2, v8
	v_mov_b32_e32 v249, 0
	v_lshl_add_u64 v[248:249], v[20:21], 0, v[248:249]
	global_load_dword v184, v[248:249], off
	global_load_dword v185, v[248:249], off offset:8
	global_load_dword v186, v[248:249], off offset:16
	global_load_dword v187, v[248:249], off offset:24
	global_load_dword v232, v[248:249], off offset:32
	global_load_dword v233, v[248:249], off offset:40
	global_load_dword v234, v[248:249], off offset:48
	global_load_dword v235, v[248:249], off offset:56
	global_load_dword v236, v[248:249], off offset:64
	global_load_dword v237, v[248:249], off offset:72
	global_load_dword v238, v[248:249], off offset:80
	global_load_dword v239, v[248:249], off offset:88
	global_load_dword v240, v[248:249], off offset:96
	global_load_dword v241, v[248:249], off offset:104
	global_load_dword v242, v[248:249], off offset:112
	global_load_dword v243, v[248:249], off offset:120
	s_waitcnt vmcnt(15)
	v_mul_f32_e32 v112, v184, v112
	v_mul_f32_e32 v113, v184, v113
	v_mul_f32_e32 v114, v184, v114
	v_mul_f32_e32 v115, v184, v115
	s_mov_b64 exec, s[12:13]
	v_cvt_pk_bf16_f32 v250, v112, v112
	ds_write_b16 v52, v250 offset:0
	v_cvt_pk_bf16_f32 v251, v113, v113
	ds_write_b16 v52, v251 offset:260
	v_cvt_pk_bf16_f32 v250, v114, v114
	ds_write_b16 v52, v250 offset:520
	v_cvt_pk_bf16_f32 v251, v115, v115
	ds_write_b16 v52, v251 offset:780
	s_waitcnt vmcnt(14)
	s_mov_b64 exec, s[16:17]
	v_mul_f32_e32 v116, v185, v116
	v_mul_f32_e32 v117, v185, v117
	v_mul_f32_e32 v118, v185, v118
	v_mul_f32_e32 v119, v185, v119
	s_mov_b64 exec, s[12:13]
	v_cvt_pk_bf16_f32 v250, v116, v116
	ds_write_b16 v52, v250 offset:4
	v_cvt_pk_bf16_f32 v251, v117, v117
	ds_write_b16 v52, v251 offset:264
	v_cvt_pk_bf16_f32 v250, v118, v118
	ds_write_b16 v52, v250 offset:524
	v_cvt_pk_bf16_f32 v251, v119, v119
	ds_write_b16 v52, v251 offset:784
	s_waitcnt vmcnt(13)
	s_mov_b64 exec, s[16:17]
	v_mul_f32_e32 v120, v186, v120
	v_mul_f32_e32 v121, v186, v121
	v_mul_f32_e32 v122, v186, v122
	v_mul_f32_e32 v123, v186, v123
	s_mov_b64 exec, s[12:13]
	v_cvt_pk_bf16_f32 v250, v120, v120
	ds_write_b16 v52, v250 offset:8
	v_cvt_pk_bf16_f32 v251, v121, v121
	ds_write_b16 v52, v251 offset:268
	v_cvt_pk_bf16_f32 v250, v122, v122
	ds_write_b16 v52, v250 offset:528
	v_cvt_pk_bf16_f32 v251, v123, v123
	ds_write_b16 v52, v251 offset:788
	s_waitcnt vmcnt(12)
	s_mov_b64 exec, s[16:17]
	v_mul_f32_e32 v124, v187, v124
	v_mul_f32_e32 v125, v187, v125
	v_mul_f32_e32 v126, v187, v126
	v_mul_f32_e32 v127, v187, v127
	s_mov_b64 exec, s[12:13]
	v_cvt_pk_bf16_f32 v250, v124, v124
	ds_write_b16 v52, v250 offset:12
	v_cvt_pk_bf16_f32 v251, v125, v125
	ds_write_b16 v52, v251 offset:272
	v_cvt_pk_bf16_f32 v250, v126, v126
	ds_write_b16 v52, v250 offset:532
	v_cvt_pk_bf16_f32 v251, v127, v127
	ds_write_b16 v52, v251 offset:792
	s_waitcnt vmcnt(11)
	s_mov_b64 exec, s[16:17]
	v_mul_f32_e32 v136, v232, v136
	v_mul_f32_e32 v137, v232, v137
	v_mul_f32_e32 v138, v232, v138
	v_mul_f32_e32 v139, v232, v139
	s_mov_b64 exec, s[12:13]
	v_cvt_pk_bf16_f32 v250, v136, v136
	ds_write_b16 v52, v250 offset:16
	v_cvt_pk_bf16_f32 v251, v137, v137
	ds_write_b16 v52, v251 offset:276
	v_cvt_pk_bf16_f32 v250, v138, v138
	ds_write_b16 v52, v250 offset:536
	v_cvt_pk_bf16_f32 v251, v139, v139
	ds_write_b16 v52, v251 offset:796
	s_waitcnt vmcnt(10)
	s_mov_b64 exec, s[16:17]
	v_mul_f32_e32 v140, v233, v140
	v_mul_f32_e32 v141, v233, v141
	v_mul_f32_e32 v142, v233, v142
	v_mul_f32_e32 v143, v233, v143
	s_mov_b64 exec, s[12:13]
	v_cvt_pk_bf16_f32 v250, v140, v140
	ds_write_b16 v52, v250 offset:20
	v_cvt_pk_bf16_f32 v251, v141, v141
	ds_write_b16 v52, v251 offset:280
	v_cvt_pk_bf16_f32 v250, v142, v142
	ds_write_b16 v52, v250 offset:540
	v_cvt_pk_bf16_f32 v251, v143, v143
	ds_write_b16 v52, v251 offset:800
	s_waitcnt vmcnt(9)
	s_mov_b64 exec, s[16:17]
	v_mul_f32_e32 v144, v234, v144
	v_mul_f32_e32 v145, v234, v145
	v_mul_f32_e32 v146, v234, v146
	v_mul_f32_e32 v147, v234, v147
	s_mov_b64 exec, s[12:13]
	v_cvt_pk_bf16_f32 v250, v144, v144
	ds_write_b16 v52, v250 offset:24
	v_cvt_pk_bf16_f32 v251, v145, v145
	ds_write_b16 v52, v251 offset:284
	v_cvt_pk_bf16_f32 v250, v146, v146
	ds_write_b16 v52, v250 offset:544
	v_cvt_pk_bf16_f32 v251, v147, v147
	ds_write_b16 v52, v251 offset:804
	s_waitcnt vmcnt(8)
	s_mov_b64 exec, s[16:17]
	v_mul_f32_e32 v148, v235, v148
	v_mul_f32_e32 v149, v235, v149
	v_mul_f32_e32 v150, v235, v150
	v_mul_f32_e32 v151, v235, v151
	s_mov_b64 exec, s[12:13]
	v_cvt_pk_bf16_f32 v250, v148, v148
	ds_write_b16 v52, v250 offset:28
	v_cvt_pk_bf16_f32 v251, v149, v149
	ds_write_b16 v52, v251 offset:288
	v_cvt_pk_bf16_f32 v250, v150, v150
	ds_write_b16 v52, v250 offset:548
	v_cvt_pk_bf16_f32 v251, v151, v151
	ds_write_b16 v52, v251 offset:808
	s_waitcnt vmcnt(7)
	s_mov_b64 exec, s[16:17]
	v_mul_f32_e32 v152, v236, v152
	v_mul_f32_e32 v153, v236, v153
	v_mul_f32_e32 v154, v236, v154
	v_mul_f32_e32 v155, v236, v155
	s_mov_b64 exec, s[12:13]
	v_cvt_pk_bf16_f32 v250, v152, v152
	ds_write_b16 v52, v250 offset:32
	v_cvt_pk_bf16_f32 v251, v153, v153
	ds_write_b16 v52, v251 offset:292
	v_cvt_pk_bf16_f32 v250, v154, v154
	ds_write_b16 v52, v250 offset:552
	v_cvt_pk_bf16_f32 v251, v155, v155
	ds_write_b16 v52, v251 offset:812
	s_waitcnt vmcnt(6)
	s_mov_b64 exec, s[16:17]
	v_mul_f32_e32 v156, v237, v156
	v_mul_f32_e32 v157, v237, v157
	v_mul_f32_e32 v158, v237, v158
	v_mul_f32_e32 v159, v237, v159
	s_mov_b64 exec, s[12:13]
	v_cvt_pk_bf16_f32 v250, v156, v156
	ds_write_b16 v52, v250 offset:36
	v_cvt_pk_bf16_f32 v251, v157, v157
	ds_write_b16 v52, v251 offset:296
	v_cvt_pk_bf16_f32 v250, v158, v158
	ds_write_b16 v52, v250 offset:556
	v_cvt_pk_bf16_f32 v251, v159, v159
	ds_write_b16 v52, v251 offset:816
	s_waitcnt vmcnt(5)
	s_mov_b64 exec, s[16:17]
	v_mul_f32_e32 v160, v238, v160
	v_mul_f32_e32 v161, v238, v161
	v_mul_f32_e32 v162, v238, v162
	v_mul_f32_e32 v163, v238, v163
	s_mov_b64 exec, s[12:13]
	v_cvt_pk_bf16_f32 v250, v160, v160
	ds_write_b16 v52, v250 offset:40
	v_cvt_pk_bf16_f32 v251, v161, v161
	ds_write_b16 v52, v251 offset:300
	v_cvt_pk_bf16_f32 v250, v162, v162
	ds_write_b16 v52, v250 offset:560
	v_cvt_pk_bf16_f32 v251, v163, v163
	ds_write_b16 v52, v251 offset:820
	s_waitcnt vmcnt(4)
	s_mov_b64 exec, s[16:17]
	v_mul_f32_e32 v164, v239, v164
	v_mul_f32_e32 v165, v239, v165
	v_mul_f32_e32 v166, v239, v166
	v_mul_f32_e32 v167, v239, v167
	s_mov_b64 exec, s[12:13]
	v_cvt_pk_bf16_f32 v250, v164, v164
	ds_write_b16 v52, v250 offset:44
	v_cvt_pk_bf16_f32 v251, v165, v165
	ds_write_b16 v52, v251 offset:304
	v_cvt_pk_bf16_f32 v250, v166, v166
	ds_write_b16 v52, v250 offset:564
	v_cvt_pk_bf16_f32 v251, v167, v167
	ds_write_b16 v52, v251 offset:824
	s_waitcnt vmcnt(3)
	s_mov_b64 exec, s[16:17]
	v_mul_f32_e32 v168, v240, v168
	v_mul_f32_e32 v169, v240, v169
	v_mul_f32_e32 v170, v240, v170
	v_mul_f32_e32 v171, v240, v171
	s_mov_b64 exec, s[12:13]
	v_cvt_pk_bf16_f32 v250, v168, v168
	ds_write_b16 v52, v250 offset:48
	v_cvt_pk_bf16_f32 v251, v169, v169
	ds_write_b16 v52, v251 offset:308
	v_cvt_pk_bf16_f32 v250, v170, v170
	ds_write_b16 v52, v250 offset:568
	v_cvt_pk_bf16_f32 v251, v171, v171
	ds_write_b16 v52, v251 offset:828
	s_waitcnt vmcnt(2)
	s_mov_b64 exec, s[16:17]
	v_mul_f32_e32 v172, v241, v172
	v_mul_f32_e32 v173, v241, v173
	v_mul_f32_e32 v174, v241, v174
	v_mul_f32_e32 v175, v241, v175
	s_mov_b64 exec, s[12:13]
	v_cvt_pk_bf16_f32 v250, v172, v172
	ds_write_b16 v52, v250 offset:52
	v_cvt_pk_bf16_f32 v251, v173, v173
	ds_write_b16 v52, v251 offset:312
	v_cvt_pk_bf16_f32 v250, v174, v174
	ds_write_b16 v52, v250 offset:572
	v_cvt_pk_bf16_f32 v251, v175, v175
	ds_write_b16 v52, v251 offset:832
	s_waitcnt vmcnt(1)
	s_mov_b64 exec, s[16:17]
	v_mul_f32_e32 v176, v242, v176
	v_mul_f32_e32 v177, v242, v177
	v_mul_f32_e32 v178, v242, v178
	v_mul_f32_e32 v179, v242, v179
	s_mov_b64 exec, s[12:13]
	v_cvt_pk_bf16_f32 v250, v176, v176
	ds_write_b16 v52, v250 offset:56
	v_cvt_pk_bf16_f32 v251, v177, v177
	ds_write_b16 v52, v251 offset:316
	v_cvt_pk_bf16_f32 v250, v178, v178
	ds_write_b16 v52, v250 offset:576
	v_cvt_pk_bf16_f32 v251, v179, v179
	ds_write_b16 v52, v251 offset:836
	s_waitcnt vmcnt(0)
	s_mov_b64 exec, s[16:17]
	v_mul_f32_e32 v180, v243, v180
	v_mul_f32_e32 v181, v243, v181
	v_mul_f32_e32 v182, v243, v182
	v_mul_f32_e32 v183, v243, v183
	s_mov_b64 exec, s[12:13]
	v_cvt_pk_bf16_f32 v250, v180, v180
	ds_write_b16 v52, v250 offset:60
	v_cvt_pk_bf16_f32 v251, v181, v181
	ds_write_b16 v52, v251 offset:320
	v_cvt_pk_bf16_f32 v250, v182, v182
	ds_write_b16 v52, v250 offset:580
	v_cvt_pk_bf16_f32 v251, v183, v183
	ds_write_b16 v52, v251 offset:840
	s_mov_b32 s24, 32
	v_add_u32_e32 v52, 64, v52
	v_lshl_add_u64 v[26:27], v[26:27], 0, 64
	v_lshl_add_u64 v[26:27], v[26:27], 0, 64
	s_branch .LBB0_1225

.LBB0_1325:
	s_mov_b64 s[0:1], exec
	v_lshlrev_b32_e32 v160, 2, v128
	v_lshlrev_b32_e32 v161, 2, v128
	v_mul_u32_u24_e32 v162, 48, v128
	global_load_dword v142, v160, s[54:55]
	global_load_dword v143, v160, s[54:55] offset:2048
	v_add_u32_e32 v160, 0x1000, v160
	global_load_dword v144, v160, s[54:55]
	global_load_dword v145, v160, s[54:55] offset:2048
	v_add_u32_e32 v160, 0x1000, v160
	global_load_dword v146, v160, s[54:55]
	global_load_dword v147, v160, s[54:55] offset:2048
	v_add_u32_e32 v160, 0x1000, v160
	global_load_dword v148, v160, s[54:55]
	global_load_dword v149, v160, s[54:55] offset:2048
	v_add_u32_e32 v160, 0x1000, v160
	global_load_dword v150, v160, s[54:55]
	global_load_dword v151, v160, s[54:55] offset:2048
	v_add_u32_e32 v160, 0x1000, v160
	global_load_dword v152, v160, s[54:55]
	global_load_dword v153, v160, s[54:55] offset:2048
	v_add_u32_e32 v160, 0x1000, v160
	global_load_dword v154, v160, s[54:55]
	global_load_dword v155, v160, s[54:55] offset:2048
	v_add_u32_e32 v160, 0x1000, v160
	global_load_dword v156, v160, s[54:55]
	global_load_dword v157, v160, s[54:55] offset:2048
	global_load_dword v158, v161, s[58:59]
	global_load_dword v159, v161, s[58:59] offset:2048
	s_waitcnt vmcnt(17)
	v_mul_f32_e32 v42, 0xbfb8aa3b, v142
	v_fma_f32 v43, v142, s27, -v42
	v_rndne_f32_e32 v44, v42
	v_fmac_f32_e32 v43, 0xb2a5705f, v142
	v_sub_f32_e32 v42, v42, v44
	v_add_f32_e32 v42, v42, v43
	v_cvt_i32_f32_e32 v44, v44
	v_exp_f32_e32 v42, v42
	v_cmp_nlt_f32_e32 vcc, s28, v142
	v_ldexp_f32 v42, v42, v44
	s_nop 0
	v_cndmask_b32_e32 v42, 0, v42, vcc
	v_cmp_ngt_f32_e32 vcc, s29, v142
	s_nop 1
	v_cndmask_b32_e32 v42, v94, v42, vcc
	v_add_f32_e32 v42, 1.0, v42
	v_div_scale_f32 v43, s[16:17], v42, v42, v142
	v_rcp_f32_e32 v44, v43
	v_div_scale_f32 v45, vcc, v142, v42, v142
	v_fma_f32 v46, -v43, v44, 1.0
	v_fmac_f32_e32 v44, v46, v44
	v_mul_f32_e32 v46, v45, v44
	v_fma_f32 v47, -v43, v46, v45
	v_fmac_f32_e32 v46, v47, v44
	v_fma_f32 v43, -v43, v46, v45
	v_div_fmas_f32 v43, v43, v44, v46
	v_div_fixup_f32 v0, v43, v42, v142
	ds_write_b32 v162, v0 offset:0
	s_waitcnt vmcnt(16)
	v_mul_f32_e32 v42, 0xbfb8aa3b, v143
	v_fma_f32 v43, v143, s27, -v42
	v_rndne_f32_e32 v44, v42
	v_fmac_f32_e32 v43, 0xb2a5705f, v143
	v_sub_f32_e32 v42, v42, v44
	v_add_f32_e32 v42, v42, v43
	v_cvt_i32_f32_e32 v44, v44
	v_exp_f32_e32 v42, v42
	v_cmp_nlt_f32_e32 vcc, s28, v143
	v_ldexp_f32 v42, v42, v44
	s_nop 0
	v_cndmask_b32_e32 v42, 0, v42, vcc
	v_cmp_ngt_f32_e32 vcc, s29, v143
	s_nop 1
	v_cndmask_b32_e32 v42, v94, v42, vcc
	v_add_f32_e32 v42, 1.0, v42
	v_div_scale_f32 v43, s[16:17], v42, v42, v143
	v_rcp_f32_e32 v44, v43
	v_div_scale_f32 v45, vcc, v143, v42, v143
	v_fma_f32 v46, -v43, v44, 1.0
	v_fmac_f32_e32 v44, v46, v44
	v_mul_f32_e32 v46, v45, v44
	v_fma_f32 v47, -v43, v46, v45
	v_fmac_f32_e32 v46, v47, v44
	v_fma_f32 v43, -v43, v46, v45
	v_div_fmas_f32 v43, v43, v44, v46
	v_div_fixup_f32 v0, v43, v42, v143
	ds_write_b32 v162, v0 offset:24576
	s_waitcnt vmcnt(15)
	v_mul_f32_e32 v42, 0xbfb8aa3b, v144
	v_fma_f32 v43, v144, s27, -v42
	v_rndne_f32_e32 v44, v42
	v_fmac_f32_e32 v43, 0xb2a5705f, v144
	v_sub_f32_e32 v42, v42, v44
	v_add_f32_e32 v42, v42, v43
	v_cvt_i32_f32_e32 v44, v44
	v_exp_f32_e32 v42, v42
	v_cmp_nlt_f32_e32 vcc, s28, v144
	v_ldexp_f32 v42, v42, v44
	s_nop 0
	v_cndmask_b32_e32 v42, 0, v42, vcc
	v_cmp_ngt_f32_e32 vcc, s29, v144
	s_nop 1
	v_cndmask_b32_e32 v42, v94, v42, vcc
	v_add_f32_e32 v42, 1.0, v42
	v_div_scale_f32 v43, s[16:17], v42, v42, v144
	v_rcp_f32_e32 v44, v43
	v_div_scale_f32 v45, vcc, v144, v42, v144
	v_fma_f32 v46, -v43, v44, 1.0
	v_fmac_f32_e32 v44, v46, v44
	v_mul_f32_e32 v46, v45, v44
	v_fma_f32 v47, -v43, v46, v45
	v_fmac_f32_e32 v46, v47, v44
	v_fma_f32 v43, -v43, v46, v45
	v_div_fmas_f32 v43, v43, v44, v46
	v_div_fixup_f32 v0, v43, v42, v144
	ds_write_b32 v162, v0 offset:4
	s_waitcnt vmcnt(14)
	v_mul_f32_e32 v42, 0xbfb8aa3b, v145
	v_fma_f32 v43, v145, s27, -v42
	v_rndne_f32_e32 v44, v42
	v_fmac_f32_e32 v43, 0xb2a5705f, v145
	v_sub_f32_e32 v42, v42, v44
	v_add_f32_e32 v42, v42, v43
	v_cvt_i32_f32_e32 v44, v44
	v_exp_f32_e32 v42, v42
	v_cmp_nlt_f32_e32 vcc, s28, v145
	v_ldexp_f32 v42, v42, v44
	s_nop 0
	v_cndmask_b32_e32 v42, 0, v42, vcc
	v_cmp_ngt_f32_e32 vcc, s29, v145
	s_nop 1
	v_cndmask_b32_e32 v42, v94, v42, vcc
	v_add_f32_e32 v42, 1.0, v42
	v_div_scale_f32 v43, s[16:17], v42, v42, v145
	v_rcp_f32_e32 v44, v43
	v_div_scale_f32 v45, vcc, v145, v42, v145
	v_fma_f32 v46, -v43, v44, 1.0
	v_fmac_f32_e32 v44, v46, v44
	v_mul_f32_e32 v46, v45, v44
	v_fma_f32 v47, -v43, v46, v45
	v_fmac_f32_e32 v46, v47, v44
	v_fma_f32 v43, -v43, v46, v45
	v_div_fmas_f32 v43, v43, v44, v46
	v_div_fixup_f32 v0, v43, v42, v145
	ds_write_b32 v162, v0 offset:24580
	s_waitcnt vmcnt(13)
	v_mul_f32_e32 v42, 0xbfb8aa3b, v146
	v_fma_f32 v43, v146, s27, -v42
	v_rndne_f32_e32 v44, v42
	v_fmac_f32_e32 v43, 0xb2a5705f, v146
	v_sub_f32_e32 v42, v42, v44
	v_add_f32_e32 v42, v42, v43
	v_cvt_i32_f32_e32 v44, v44
	v_exp_f32_e32 v42, v42
	v_cmp_nlt_f32_e32 vcc, s28, v146
	v_ldexp_f32 v42, v42, v44
	s_nop 0
	v_cndmask_b32_e32 v42, 0, v42, vcc
	v_cmp_ngt_f32_e32 vcc, s29, v146
	s_nop 1
	v_cndmask_b32_e32 v42, v94, v42, vcc
	v_add_f32_e32 v42, 1.0, v42
	v_div_scale_f32 v43, s[16:17], v42, v42, v146
	v_rcp_f32_e32 v44, v43
	v_div_scale_f32 v45, vcc, v146, v42, v146
	v_fma_f32 v46, -v43, v44, 1.0
	v_fmac_f32_e32 v44, v46, v44
	v_mul_f32_e32 v46, v45, v44
	v_fma_f32 v47, -v43, v46, v45
	v_fmac_f32_e32 v46, v47, v44
	v_fma_f32 v43, -v43, v46, v45
	v_div_fmas_f32 v43, v43, v44, v46
	v_div_fixup_f32 v0, v43, v42, v146
	ds_write_b32 v162, v0 offset:8
	s_waitcnt vmcnt(12)
	v_mul_f32_e32 v42, 0xbfb8aa3b, v147
	v_fma_f32 v43, v147, s27, -v42
	v_rndne_f32_e32 v44, v42
	v_fmac_f32_e32 v43, 0xb2a5705f, v147
	v_sub_f32_e32 v42, v42, v44
	v_add_f32_e32 v42, v42, v43
	v_cvt_i32_f32_e32 v44, v44
	v_exp_f32_e32 v42, v42
	v_cmp_nlt_f32_e32 vcc, s28, v147
	v_ldexp_f32 v42, v42, v44
	s_nop 0
	v_cndmask_b32_e32 v42, 0, v42, vcc
	v_cmp_ngt_f32_e32 vcc, s29, v147
	s_nop 1
	v_cndmask_b32_e32 v42, v94, v42, vcc
	v_add_f32_e32 v42, 1.0, v42
	v_div_scale_f32 v43, s[16:17], v42, v42, v147
	v_rcp_f32_e32 v44, v43
	v_div_scale_f32 v45, vcc, v147, v42, v147
	v_fma_f32 v46, -v43, v44, 1.0
	v_fmac_f32_e32 v44, v46, v44
	v_mul_f32_e32 v46, v45, v44
	v_fma_f32 v47, -v43, v46, v45
	v_fmac_f32_e32 v46, v47, v44
	v_fma_f32 v43, -v43, v46, v45
	v_div_fmas_f32 v43, v43, v44, v46
	v_div_fixup_f32 v0, v43, v42, v147
	ds_write_b32 v162, v0 offset:24584
	s_waitcnt vmcnt(11)
	v_mul_f32_e32 v42, 0xbfb8aa3b, v148
	v_fma_f32 v43, v148, s27, -v42
	v_rndne_f32_e32 v44, v42
	v_fmac_f32_e32 v43, 0xb2a5705f, v148
	v_sub_f32_e32 v42, v42, v44
	v_add_f32_e32 v42, v42, v43
	v_cvt_i32_f32_e32 v44, v44
	v_exp_f32_e32 v42, v42
	v_cmp_nlt_f32_e32 vcc, s28, v148
	v_ldexp_f32 v42, v42, v44
	s_nop 0
	v_cndmask_b32_e32 v42, 0, v42, vcc
	v_cmp_ngt_f32_e32 vcc, s29, v148
	s_nop 1
	v_cndmask_b32_e32 v42, v94, v42, vcc
	v_add_f32_e32 v42, 1.0, v42
	v_div_scale_f32 v43, s[16:17], v42, v42, v148
	v_rcp_f32_e32 v44, v43
	v_div_scale_f32 v45, vcc, v148, v42, v148
	v_fma_f32 v46, -v43, v44, 1.0
	v_fmac_f32_e32 v44, v46, v44
	v_mul_f32_e32 v46, v45, v44
	v_fma_f32 v47, -v43, v46, v45
	v_fmac_f32_e32 v46, v47, v44
	v_fma_f32 v43, -v43, v46, v45
	v_div_fmas_f32 v43, v43, v44, v46
	v_div_fixup_f32 v0, v43, v42, v148
	ds_write_b32 v162, v0 offset:12
	s_waitcnt vmcnt(10)
	v_mul_f32_e32 v42, 0xbfb8aa3b, v149
	v_fma_f32 v43, v149, s27, -v42
	v_rndne_f32_e32 v44, v42
	v_fmac_f32_e32 v43, 0xb2a5705f, v149
	v_sub_f32_e32 v42, v42, v44
	v_add_f32_e32 v42, v42, v43
	v_cvt_i32_f32_e32 v44, v44
	v_exp_f32_e32 v42, v42
	v_cmp_nlt_f32_e32 vcc, s28, v149
	v_ldexp_f32 v42, v42, v44
	s_nop 0
	v_cndmask_b32_e32 v42, 0, v42, vcc
	v_cmp_ngt_f32_e32 vcc, s29, v149
	s_nop 1
	v_cndmask_b32_e32 v42, v94, v42, vcc
	v_add_f32_e32 v42, 1.0, v42
	v_div_scale_f32 v43, s[16:17], v42, v42, v149
	v_rcp_f32_e32 v44, v43
	v_div_scale_f32 v45, vcc, v149, v42, v149
	v_fma_f32 v46, -v43, v44, 1.0
	v_fmac_f32_e32 v44, v46, v44
	v_mul_f32_e32 v46, v45, v44
	v_fma_f32 v47, -v43, v46, v45
	v_fmac_f32_e32 v46, v47, v44
	v_fma_f32 v43, -v43, v46, v45
	v_div_fmas_f32 v43, v43, v44, v46
	v_div_fixup_f32 v0, v43, v42, v149
	ds_write_b32 v162, v0 offset:24588
	s_waitcnt vmcnt(9)
	v_mul_f32_e32 v42, 0xbfb8aa3b, v150
	v_fma_f32 v43, v150, s27, -v42
	v_rndne_f32_e32 v44, v42
	v_fmac_f32_e32 v43, 0xb2a5705f, v150
	v_sub_f32_e32 v42, v42, v44
	v_add_f32_e32 v42, v42, v43
	v_cvt_i32_f32_e32 v44, v44
	v_exp_f32_e32 v42, v42
	v_cmp_nlt_f32_e32 vcc, s28, v150
	v_ldexp_f32 v42, v42, v44
	s_nop 0
	v_cndmask_b32_e32 v42, 0, v42, vcc
	v_cmp_ngt_f32_e32 vcc, s29, v150
	s_nop 1
	v_cndmask_b32_e32 v42, v94, v42, vcc
	v_add_f32_e32 v42, 1.0, v42
	v_div_scale_f32 v43, s[16:17], v42, v42, v150
	v_rcp_f32_e32 v44, v43
	v_div_scale_f32 v45, vcc, v150, v42, v150
	v_fma_f32 v46, -v43, v44, 1.0
	v_fmac_f32_e32 v44, v46, v44
	v_mul_f32_e32 v46, v45, v44
	v_fma_f32 v47, -v43, v46, v45
	v_fmac_f32_e32 v46, v47, v44
	v_fma_f32 v43, -v43, v46, v45
	v_div_fmas_f32 v43, v43, v44, v46
	v_div_fixup_f32 v0, v43, v42, v150
	ds_write_b32 v162, v0 offset:16
	s_waitcnt vmcnt(8)
	v_mul_f32_e32 v42, 0xbfb8aa3b, v151
	v_fma_f32 v43, v151, s27, -v42
	v_rndne_f32_e32 v44, v42
	v_fmac_f32_e32 v43, 0xb2a5705f, v151
	v_sub_f32_e32 v42, v42, v44
	v_add_f32_e32 v42, v42, v43
	v_cvt_i32_f32_e32 v44, v44
	v_exp_f32_e32 v42, v42
	v_cmp_nlt_f32_e32 vcc, s28, v151
	v_ldexp_f32 v42, v42, v44
	s_nop 0
	v_cndmask_b32_e32 v42, 0, v42, vcc
	v_cmp_ngt_f32_e32 vcc, s29, v151
	s_nop 1
	v_cndmask_b32_e32 v42, v94, v42, vcc
	v_add_f32_e32 v42, 1.0, v42
	v_div_scale_f32 v43, s[16:17], v42, v42, v151
	v_rcp_f32_e32 v44, v43
	v_div_scale_f32 v45, vcc, v151, v42, v151
	v_fma_f32 v46, -v43, v44, 1.0
	v_fmac_f32_e32 v44, v46, v44
	v_mul_f32_e32 v46, v45, v44
	v_fma_f32 v47, -v43, v46, v45
	v_fmac_f32_e32 v46, v47, v44
	v_fma_f32 v43, -v43, v46, v45
	v_div_fmas_f32 v43, v43, v44, v46
	v_div_fixup_f32 v0, v43, v42, v151
	ds_write_b32 v162, v0 offset:24592
	s_waitcnt vmcnt(7)
	v_mul_f32_e32 v42, 0xbfb8aa3b, v152
	v_fma_f32 v43, v152, s27, -v42
	v_rndne_f32_e32 v44, v42
	v_fmac_f32_e32 v43, 0xb2a5705f, v152
	v_sub_f32_e32 v42, v42, v44
	v_add_f32_e32 v42, v42, v43
	v_cvt_i32_f32_e32 v44, v44
	v_exp_f32_e32 v42, v42
	v_cmp_nlt_f32_e32 vcc, s28, v152
	v_ldexp_f32 v42, v42, v44
	s_nop 0
	v_cndmask_b32_e32 v42, 0, v42, vcc
	v_cmp_ngt_f32_e32 vcc, s29, v152
	s_nop 1
	v_cndmask_b32_e32 v42, v94, v42, vcc
	v_add_f32_e32 v42, 1.0, v42
	v_div_scale_f32 v43, s[16:17], v42, v42, v152
	v_rcp_f32_e32 v44, v43
	v_div_scale_f32 v45, vcc, v152, v42, v152
	v_fma_f32 v46, -v43, v44, 1.0
	v_fmac_f32_e32 v44, v46, v44
	v_mul_f32_e32 v46, v45, v44
	v_fma_f32 v47, -v43, v46, v45
	v_fmac_f32_e32 v46, v47, v44
	v_fma_f32 v43, -v43, v46, v45
	v_div_fmas_f32 v43, v43, v44, v46
	v_div_fixup_f32 v0, v43, v42, v152
	ds_write_b32 v162, v0 offset:20
	s_waitcnt vmcnt(6)
	v_mul_f32_e32 v42, 0xbfb8aa3b, v153
	v_fma_f32 v43, v153, s27, -v42
	v_rndne_f32_e32 v44, v42
	v_fmac_f32_e32 v43, 0xb2a5705f, v153
	v_sub_f32_e32 v42, v42, v44
	v_add_f32_e32 v42, v42, v43
	v_cvt_i32_f32_e32 v44, v44
	v_exp_f32_e32 v42, v42
	v_cmp_nlt_f32_e32 vcc, s28, v153
	v_ldexp_f32 v42, v42, v44
	s_nop 0
	v_cndmask_b32_e32 v42, 0, v42, vcc
	v_cmp_ngt_f32_e32 vcc, s29, v153
	s_nop 1
	v_cndmask_b32_e32 v42, v94, v42, vcc
	v_add_f32_e32 v42, 1.0, v42
	v_div_scale_f32 v43, s[16:17], v42, v42, v153
	v_rcp_f32_e32 v44, v43
	v_div_scale_f32 v45, vcc, v153, v42, v153
	v_fma_f32 v46, -v43, v44, 1.0
	v_fmac_f32_e32 v44, v46, v44
	v_mul_f32_e32 v46, v45, v44
	v_fma_f32 v47, -v43, v46, v45
	v_fmac_f32_e32 v46, v47, v44
	v_fma_f32 v43, -v43, v46, v45
	v_div_fmas_f32 v43, v43, v44, v46
	v_div_fixup_f32 v0, v43, v42, v153
	ds_write_b32 v162, v0 offset:24596
	s_waitcnt vmcnt(5)
	v_mul_f32_e32 v42, 0xbfb8aa3b, v154
	v_fma_f32 v43, v154, s27, -v42
	v_rndne_f32_e32 v44, v42
	v_fmac_f32_e32 v43, 0xb2a5705f, v154
	v_sub_f32_e32 v42, v42, v44
	v_add_f32_e32 v42, v42, v43
	v_cvt_i32_f32_e32 v44, v44
	v_exp_f32_e32 v42, v42
	v_cmp_nlt_f32_e32 vcc, s28, v154
	v_ldexp_f32 v42, v42, v44
	s_nop 0
	v_cndmask_b32_e32 v42, 0, v42, vcc
	v_cmp_ngt_f32_e32 vcc, s29, v154
	s_nop 1
	v_cndmask_b32_e32 v42, v94, v42, vcc
	v_add_f32_e32 v42, 1.0, v42
	v_div_scale_f32 v43, s[16:17], v42, v42, v154
	v_rcp_f32_e32 v44, v43
	v_div_scale_f32 v45, vcc, v154, v42, v154
	v_fma_f32 v46, -v43, v44, 1.0
	v_fmac_f32_e32 v44, v46, v44
	v_mul_f32_e32 v46, v45, v44
	v_fma_f32 v47, -v43, v46, v45
	v_fmac_f32_e32 v46, v47, v44
	v_fma_f32 v43, -v43, v46, v45
	v_div_fmas_f32 v43, v43, v44, v46
	v_div_fixup_f32 v0, v43, v42, v154
	ds_write_b32 v162, v0 offset:24
	s_waitcnt vmcnt(4)
	v_mul_f32_e32 v42, 0xbfb8aa3b, v155
	v_fma_f32 v43, v155, s27, -v42
	v_rndne_f32_e32 v44, v42
	v_fmac_f32_e32 v43, 0xb2a5705f, v155
	v_sub_f32_e32 v42, v42, v44
	v_add_f32_e32 v42, v42, v43
	v_cvt_i32_f32_e32 v44, v44
	v_exp_f32_e32 v42, v42
	v_cmp_nlt_f32_e32 vcc, s28, v155
	v_ldexp_f32 v42, v42, v44
	s_nop 0
	v_cndmask_b32_e32 v42, 0, v42, vcc
	v_cmp_ngt_f32_e32 vcc, s29, v155
	s_nop 1
	v_cndmask_b32_e32 v42, v94, v42, vcc
	v_add_f32_e32 v42, 1.0, v42
	v_div_scale_f32 v43, s[16:17], v42, v42, v155
	v_rcp_f32_e32 v44, v43
	v_div_scale_f32 v45, vcc, v155, v42, v155
	v_fma_f32 v46, -v43, v44, 1.0
	v_fmac_f32_e32 v44, v46, v44
	v_mul_f32_e32 v46, v45, v44
	v_fma_f32 v47, -v43, v46, v45
	v_fmac_f32_e32 v46, v47, v44
	v_fma_f32 v43, -v43, v46, v45
	v_div_fmas_f32 v43, v43, v44, v46
	v_div_fixup_f32 v0, v43, v42, v155
	ds_write_b32 v162, v0 offset:24600
	s_waitcnt vmcnt(3)
	v_mul_f32_e32 v42, 0xbfb8aa3b, v156
	v_fma_f32 v43, v156, s27, -v42
	v_rndne_f32_e32 v44, v42
	v_fmac_f32_e32 v43, 0xb2a5705f, v156
	v_sub_f32_e32 v42, v42, v44
	v_add_f32_e32 v42, v42, v43
	v_cvt_i32_f32_e32 v44, v44
	v_exp_f32_e32 v42, v42
	v_cmp_nlt_f32_e32 vcc, s28, v156
	v_ldexp_f32 v42, v42, v44
	s_nop 0
	v_cndmask_b32_e32 v42, 0, v42, vcc
	v_cmp_ngt_f32_e32 vcc, s29, v156
	s_nop 1
	v_cndmask_b32_e32 v42, v94, v42, vcc
	v_add_f32_e32 v42, 1.0, v42
	v_div_scale_f32 v43, s[16:17], v42, v42, v156
	v_rcp_f32_e32 v44, v43
	v_div_scale_f32 v45, vcc, v156, v42, v156
	v_fma_f32 v46, -v43, v44, 1.0
	v_fmac_f32_e32 v44, v46, v44
	v_mul_f32_e32 v46, v45, v44
	v_fma_f32 v47, -v43, v46, v45
	v_fmac_f32_e32 v46, v47, v44
	v_fma_f32 v43, -v43, v46, v45
	v_div_fmas_f32 v43, v43, v44, v46
	v_div_fixup_f32 v0, v43, v42, v156
	ds_write_b32 v162, v0 offset:28
	s_waitcnt vmcnt(2)
	v_mul_f32_e32 v42, 0xbfb8aa3b, v157
	v_fma_f32 v43, v157, s27, -v42
	v_rndne_f32_e32 v44, v42
	v_fmac_f32_e32 v43, 0xb2a5705f, v157
	v_sub_f32_e32 v42, v42, v44
	v_add_f32_e32 v42, v42, v43
	v_cvt_i32_f32_e32 v44, v44
	v_exp_f32_e32 v42, v42
	v_cmp_nlt_f32_e32 vcc, s28, v157
	v_ldexp_f32 v42, v42, v44
	s_nop 0
	v_cndmask_b32_e32 v42, 0, v42, vcc
	v_cmp_ngt_f32_e32 vcc, s29, v157
	s_nop 1
	v_cndmask_b32_e32 v42, v94, v42, vcc
	v_add_f32_e32 v42, 1.0, v42
	v_div_scale_f32 v43, s[16:17], v42, v42, v157
	v_rcp_f32_e32 v44, v43
	v_div_scale_f32 v45, vcc, v157, v42, v157
	v_fma_f32 v46, -v43, v44, 1.0
	v_fmac_f32_e32 v44, v46, v44
	v_mul_f32_e32 v46, v45, v44
	v_fma_f32 v47, -v43, v46, v45
	v_fmac_f32_e32 v46, v47, v44
	v_fma_f32 v43, -v43, v46, v45
	v_div_fmas_f32 v43, v43, v44, v46
	v_div_fixup_f32 v0, v43, v42, v157
	ds_write_b32 v162, v0 offset:24604
	s_waitcnt vmcnt(1)
	v_mul_f32_e32 v42, 0xbfb8aa3b, v158
	v_fma_f32 v43, v158, s27, -v42
	v_rndne_f32_e32 v44, v42
	v_fmac_f32_e32 v43, 0xb2a5705f, v158
	v_sub_f32_e32 v42, v42, v44
	v_add_f32_e32 v42, v42, v43
	v_cvt_i32_f32_e32 v44, v44
	v_exp_f32_e32 v42, v42
	v_cmp_nlt_f32_e32 vcc, s28, v158
	v_ldexp_f32 v42, v42, v44
	s_nop 0
	v_cndmask_b32_e32 v42, 0, v42, vcc
	v_cmp_ngt_f32_e32 vcc, s29, v158
	s_nop 1
	v_cndmask_b32_e32 v42, v94, v42, vcc
	v_add_f32_e32 v42, 1.0, v42
	v_div_scale_f32 v43, s[16:17], v42, v42, v158
	v_rcp_f32_e32 v44, v43
	v_div_scale_f32 v45, vcc, v158, v42, v158
	v_fma_f32 v46, -v43, v44, 1.0
	v_fmac_f32_e32 v44, v46, v44
	v_mul_f32_e32 v46, v45, v44
	v_fma_f32 v47, -v43, v46, v45
	v_fmac_f32_e32 v46, v47, v44
	v_fma_f32 v43, -v43, v46, v45
	v_div_fmas_f32 v43, v43, v44, v46
	v_div_fixup_f32 v0, v43, v42, v158
	ds_write_b32 v162, v0 offset:32
	s_waitcnt vmcnt(0)
	v_mul_f32_e32 v42, 0xbfb8aa3b, v159
	v_fma_f32 v43, v159, s27, -v42
	v_rndne_f32_e32 v44, v42
	v_fmac_f32_e32 v43, 0xb2a5705f, v159
	v_sub_f32_e32 v42, v42, v44
	v_add_f32_e32 v42, v42, v43
	v_cvt_i32_f32_e32 v44, v44
	v_exp_f32_e32 v42, v42
	v_cmp_nlt_f32_e32 vcc, s28, v159
	v_ldexp_f32 v42, v42, v44
	s_nop 0
	v_cndmask_b32_e32 v42, 0, v42, vcc
	v_cmp_ngt_f32_e32 vcc, s29, v159
	s_nop 1
	v_cndmask_b32_e32 v42, v94, v42, vcc
	v_add_f32_e32 v42, 1.0, v42
	v_div_scale_f32 v43, s[16:17], v42, v42, v159
	v_rcp_f32_e32 v44, v43
	v_div_scale_f32 v45, vcc, v159, v42, v159
	v_fma_f32 v46, -v43, v44, 1.0
	v_fmac_f32_e32 v44, v46, v44
	v_mul_f32_e32 v46, v45, v44
	v_fma_f32 v47, -v43, v46, v45
	v_fmac_f32_e32 v46, v47, v44
	v_fma_f32 v43, -v43, v46, v45
	v_div_fmas_f32 v43, v43, v44, v46
	v_div_fixup_f32 v0, v43, v42, v159
	ds_write_b32 v162, v0 offset:24608
